# j2 + PEER u-side last batch: row loads in saddr form (drops a 64-bit VALU add per row)
# speedup vs baseline: 1.0078x; 1.0078x over previous
; #define P4_FOR16(M) M(0) M(1) M(2) M(3) M(4) M(5) M(6) M(7) M(8) M(9) M(10) M(11) M(12) M(13) M(14) M(15)
; #define P4_U(i) { P4_DOT(b##i, part[i]); const int nk_ = __builtin_amdgcn_readlane(ksel, nb + i); P4_LOAD(b##i, Ug, nk_); }
; #define P4_U(i) { P4_DOT(b##i, part[i]); const int nk_ = __builtin_amdgcn_readlane(kn, i); P4_LOAD(b##i, nbase, nk_); }
; __device__ __forceinline__ void peer_gather_f4p(const float* X, const int* __restrict__ IDX, const float* __restrict__ G, ...
;     ...
;         {
;     ...
;             P4_FOR16(P4_U)
.LBB0_539:
	s_mov_b32 s87, s86
	s_waitcnt vmcnt(15)
	v_cvt_scalef32_pk_bf16_fp4 v42, v64, 1.0
	v_or_b32_e32 v40, s27, v44
	v_cvt_scalef32_pk_bf16_fp4 v44, v64, 1.0 op_sel:[1,0,0]
	v_cvt_scalef32_pk_bf16_fp4 v46, v64, 1.0 op_sel:[0,1,0]
	v_cvt_scalef32_pk_bf16_fp4 v48, v64, 1.0 op_sel:[1,1,0]
	v_dot2_f32_bf16 v50, v42, v6, 0
	v_dot2_f32_bf16 v42, v44, v4, 0
	v_dot2_f32_bf16 v50, v46, v10, v50
	s_cmp_eq_u32 s26, 3
	v_dot2_f32_bf16 v42, v48, v8, v42
	v_cvt_scalef32_pk_bf16_fp4 v44, v65, 1.0
	v_cvt_scalef32_pk_bf16_fp4 v46, v65, 1.0 op_sel:[1,0,0]
	v_cvt_scalef32_pk_bf16_fp4 v48, v65, 1.0 op_sel:[0,1,0]
	v_cvt_scalef32_pk_bf16_fp4 v52, v65, 1.0 op_sel:[1,1,0]
	v_readlane_b32 s26, v2, 0
	v_dot2_f32_bf16 v50, v44, v14, v50
	v_dot2_f32_bf16 v42, v46, v12, v42
	s_cselect_b32 s12, s53, s55
	v_dot2_f32_bf16 v50, v48, v18, v50
	v_dot2_f32_bf16 v42, v52, v16, v42
	v_cvt_scalef32_pk_bf16_fp4 v44, v66, 1.0
	v_cvt_scalef32_pk_bf16_fp4 v46, v66, 1.0 op_sel:[1,0,0]
	v_cvt_scalef32_pk_bf16_fp4 v48, v66, 1.0 op_sel:[0,1,0]
	v_cvt_scalef32_pk_bf16_fp4 v52, v66, 1.0 op_sel:[1,1,0]
	s_cselect_b32 s13, s52, s54
	v_dot2_f32_bf16 v50, v44, v22, v50
	v_dot2_f32_bf16 v42, v46, v20, v42
	s_lshr_b32 s26, s26, 7
	v_dot2_f32_bf16 v50, v48, v26, v50
	v_dot2_f32_bf16 v42, v52, v24, v42
	s_mov_b32 s27, s86
	v_cvt_scalef32_pk_bf16_fp4 v44, v67, 1.0
	v_cvt_scalef32_pk_bf16_fp4 v46, v67, 1.0 op_sel:[1,0,0]
	v_cvt_scalef32_pk_bf16_fp4 v48, v67, 1.0 op_sel:[0,1,0]
	v_cvt_scalef32_pk_bf16_fp4 v52, v67, 1.0 op_sel:[1,1,0]
	s_lshl_b64 s[26:27], s[26:27], 10
	v_dot2_f32_bf16 v50, v44, v30, v50
	v_dot2_f32_bf16 v42, v46, v28, v42
	s_add_u32 s26, s13, s26
	v_dot2_f32_bf16 v50, v48, v36, v50
	v_dot2_f32_bf16 v42, v52, v34, v42
	s_addc_u32 s27, s12, s27
	s_nop 2
	v_add_f32_e32 v41, v50, v42
	global_load_dwordx4 v[64:67], v32, s[26:27]
	s_waitcnt vmcnt(15)
	v_cvt_scalef32_pk_bf16_fp4 v42, v68, 1.0
	v_cvt_scalef32_pk_bf16_fp4 v44, v68, 1.0 op_sel:[1,0,0]
	v_cvt_scalef32_pk_bf16_fp4 v46, v68, 1.0 op_sel:[0,1,0]
	v_cvt_scalef32_pk_bf16_fp4 v48, v68, 1.0 op_sel:[1,1,0]
	v_dot2_f32_bf16 v50, v42, v6, 0
	v_dot2_f32_bf16 v42, v44, v4, 0
	v_dot2_f32_bf16 v50, v46, v10, v50
	v_readlane_b32 s26, v2, 1
	v_dot2_f32_bf16 v42, v48, v8, v42
	v_cvt_scalef32_pk_bf16_fp4 v44, v69, 1.0
	v_cvt_scalef32_pk_bf16_fp4 v46, v69, 1.0 op_sel:[1,0,0]
	v_cvt_scalef32_pk_bf16_fp4 v48, v69, 1.0 op_sel:[0,1,0]
	v_cvt_scalef32_pk_bf16_fp4 v52, v69, 1.0 op_sel:[1,1,0]
	s_lshr_b32 s26, s26, 7
	v_dot2_f32_bf16 v50, v44, v14, v50
	v_dot2_f32_bf16 v42, v46, v12, v42
	s_mov_b32 s27, s86
	v_dot2_f32_bf16 v50, v48, v18, v50
	v_dot2_f32_bf16 v42, v52, v16, v42
	v_cvt_scalef32_pk_bf16_fp4 v44, v70, 1.0
	v_cvt_scalef32_pk_bf16_fp4 v46, v70, 1.0 op_sel:[1,0,0]
	v_cvt_scalef32_pk_bf16_fp4 v48, v70, 1.0 op_sel:[0,1,0]
	v_cvt_scalef32_pk_bf16_fp4 v52, v70, 1.0 op_sel:[1,1,0]
	s_lshl_b64 s[26:27], s[26:27], 10
	v_dot2_f32_bf16 v50, v44, v22, v50
	v_dot2_f32_bf16 v42, v46, v20, v42
	s_add_u32 s26, s13, s26
	v_dot2_f32_bf16 v50, v48, v26, v50
	v_dot2_f32_bf16 v42, v52, v24, v42
	v_cvt_scalef32_pk_bf16_fp4 v44, v71, 1.0
	v_cvt_scalef32_pk_bf16_fp4 v46, v71, 1.0 op_sel:[1,0,0]
	v_cvt_scalef32_pk_bf16_fp4 v48, v71, 1.0 op_sel:[0,1,0]
	v_cvt_scalef32_pk_bf16_fp4 v52, v71, 1.0 op_sel:[1,1,0]
	s_addc_u32 s27, s12, s27
	v_dot2_f32_bf16 v50, v44, v30, v50
	v_dot2_f32_bf16 v42, v46, v28, v42
	v_mov_b32_e32 v38, 0
	v_dot2_f32_bf16 v50, v48, v36, v50
	v_dot2_f32_bf16 v42, v52, v34, v42
	s_nop 2
	v_add_f32_e32 v42, v50, v42
	global_load_dwordx4 v[68:71], v32, s[26:27]
	s_waitcnt vmcnt(15)
	v_cvt_scalef32_pk_bf16_fp4 v44, v72, 1.0
	v_cvt_scalef32_pk_bf16_fp4 v46, v72, 1.0 op_sel:[1,0,0]
	v_cvt_scalef32_pk_bf16_fp4 v48, v72, 1.0 op_sel:[0,1,0]
	v_cvt_scalef32_pk_bf16_fp4 v50, v72, 1.0 op_sel:[1,1,0]
	v_readlane_b32 s26, v2, 2
	v_dot2_f32_bf16 v52, v44, v6, 0
	v_dot2_f32_bf16 v44, v46, v4, 0
	v_dot2_f32_bf16 v52, v48, v10, v52
	s_lshr_b32 s26, s26, 7
	v_dot2_f32_bf16 v44, v50, v8, v44
	v_cvt_scalef32_pk_bf16_fp4 v46, v73, 1.0
	v_cvt_scalef32_pk_bf16_fp4 v48, v73, 1.0 op_sel:[1,0,0]
	v_cvt_scalef32_pk_bf16_fp4 v50, v73, 1.0 op_sel:[0,1,0]
	v_cvt_scalef32_pk_bf16_fp4 v54, v73, 1.0 op_sel:[1,1,0]
	s_mov_b32 s27, s86
	v_dot2_f32_bf16 v52, v46, v14, v52
	v_dot2_f32_bf16 v44, v48, v12, v44
	s_lshl_b64 s[26:27], s[26:27], 10
	v_dot2_f32_bf16 v52, v50, v18, v52
	v_dot2_f32_bf16 v44, v54, v16, v44
	v_cvt_scalef32_pk_bf16_fp4 v46, v74, 1.0
	v_cvt_scalef32_pk_bf16_fp4 v48, v74, 1.0 op_sel:[1,0,0]
	v_cvt_scalef32_pk_bf16_fp4 v50, v74, 1.0 op_sel:[0,1,0]
	v_cvt_scalef32_pk_bf16_fp4 v54, v74, 1.0 op_sel:[1,1,0]
	s_add_u32 s26, s13, s26
	v_dot2_f32_bf16 v52, v46, v22, v52
	v_dot2_f32_bf16 v44, v48, v20, v44
	s_addc_u32 s27, s12, s27
	v_dot2_f32_bf16 v52, v50, v26, v52
	v_dot2_f32_bf16 v44, v54, v24, v44
	v_cvt_scalef32_pk_bf16_fp4 v46, v75, 1.0
	v_cvt_scalef32_pk_bf16_fp4 v48, v75, 1.0 op_sel:[1,0,0]
	v_cvt_scalef32_pk_bf16_fp4 v50, v75, 1.0 op_sel:[0,1,0]
	v_cvt_scalef32_pk_bf16_fp4 v54, v75, 1.0 op_sel:[1,1,0]
	s_nop 0
	v_dot2_f32_bf16 v52, v46, v30, v52
	v_dot2_f32_bf16 v44, v48, v28, v44
	s_nop 0
	v_dot2_f32_bf16 v52, v50, v36, v52
	v_dot2_f32_bf16 v44, v54, v34, v44
	s_nop 0
	s_nop 2
	v_add_f32_e32 v43, v52, v44
	global_load_dwordx4 v[72:75], v32, s[26:27]
	s_waitcnt vmcnt(15)
; #define P4_FOR16(M) M(0) M(1) M(2) M(3) M(4) M(5) M(6) M(7) M(8) M(9) M(10) M(11) M(12) M(13) M(14) M(15)
; #define P4_U(i) { P4_DOT(b##i, part[i]); const int nk_ = __builtin_amdgcn_readlane(ksel, nb + i); P4_LOAD(b##i, Ug, nk_); }
; #define P4_U(i) { P4_DOT(b##i, part[i]); const int nk_ = __builtin_amdgcn_readlane(kn, i); P4_LOAD(b##i, nbase, nk_); }
; __device__ __forceinline__ void peer_gather_f4p(const float* X, const int* __restrict__ IDX, const float* __restrict__ G, ...
;     ...
;             P4_FOR16(P4_U)
	v_cvt_scalef32_pk_bf16_fp4 v44, v76, 1.0
	v_cvt_scalef32_pk_bf16_fp4 v46, v76, 1.0 op_sel:[1,0,0]
	v_cvt_scalef32_pk_bf16_fp4 v48, v76, 1.0 op_sel:[0,1,0]
	v_cvt_scalef32_pk_bf16_fp4 v50, v76, 1.0 op_sel:[1,1,0]
	v_dot2_f32_bf16 v52, v44, v6, 0
	v_dot2_f32_bf16 v44, v46, v4, 0
	v_dot2_f32_bf16 v52, v48, v10, v52
	v_readlane_b32 s26, v2, 3
	v_dot2_f32_bf16 v44, v50, v8, v44
	v_cvt_scalef32_pk_bf16_fp4 v46, v77, 1.0
	v_cvt_scalef32_pk_bf16_fp4 v48, v77, 1.0 op_sel:[1,0,0]
	v_cvt_scalef32_pk_bf16_fp4 v50, v77, 1.0 op_sel:[0,1,0]
	v_cvt_scalef32_pk_bf16_fp4 v54, v77, 1.0 op_sel:[1,1,0]
	s_lshr_b32 s26, s26, 7
	v_dot2_f32_bf16 v52, v46, v14, v52
	v_dot2_f32_bf16 v44, v48, v12, v44
	s_mov_b32 s27, s86
	v_dot2_f32_bf16 v52, v50, v18, v52
	v_dot2_f32_bf16 v44, v54, v16, v44
	v_cvt_scalef32_pk_bf16_fp4 v46, v78, 1.0
	v_cvt_scalef32_pk_bf16_fp4 v48, v78, 1.0 op_sel:[1,0,0]
	v_cvt_scalef32_pk_bf16_fp4 v50, v78, 1.0 op_sel:[0,1,0]
	v_cvt_scalef32_pk_bf16_fp4 v54, v78, 1.0 op_sel:[1,1,0]
	s_lshl_b64 s[26:27], s[26:27], 10
	v_dot2_f32_bf16 v52, v46, v22, v52
	v_dot2_f32_bf16 v44, v48, v20, v44
	s_add_u32 s26, s13, s26
	v_dot2_f32_bf16 v52, v50, v26, v52
	v_dot2_f32_bf16 v44, v54, v24, v44
	v_cvt_scalef32_pk_bf16_fp4 v46, v79, 1.0
	v_cvt_scalef32_pk_bf16_fp4 v48, v79, 1.0 op_sel:[1,0,0]
	v_cvt_scalef32_pk_bf16_fp4 v50, v79, 1.0 op_sel:[0,1,0]
	v_cvt_scalef32_pk_bf16_fp4 v54, v79, 1.0 op_sel:[1,1,0]
	s_addc_u32 s27, s12, s27
	v_dot2_f32_bf16 v52, v46, v30, v52
	v_dot2_f32_bf16 v44, v48, v28, v44
	s_nop 0
	v_dot2_f32_bf16 v52, v50, v36, v52
	v_dot2_f32_bf16 v44, v54, v34, v44
	s_nop 2
	v_add_f32_e32 v44, v52, v44
	global_load_dwordx4 v[76:79], v32, s[26:27]
	s_waitcnt vmcnt(15)
	v_cvt_scalef32_pk_bf16_fp4 v46, v80, 1.0
	v_cvt_scalef32_pk_bf16_fp4 v48, v80, 1.0 op_sel:[1,0,0]
	v_cvt_scalef32_pk_bf16_fp4 v50, v80, 1.0 op_sel:[0,1,0]
	v_cvt_scalef32_pk_bf16_fp4 v52, v80, 1.0 op_sel:[1,1,0]
	v_readlane_b32 s26, v2, 4
	v_dot2_f32_bf16 v54, v46, v6, 0
	v_dot2_f32_bf16 v46, v48, v4, 0
	v_dot2_f32_bf16 v54, v50, v10, v54
	s_lshr_b32 s26, s26, 7
	v_dot2_f32_bf16 v46, v52, v8, v46
	v_cvt_scalef32_pk_bf16_fp4 v48, v81, 1.0
	v_cvt_scalef32_pk_bf16_fp4 v50, v81, 1.0 op_sel:[1,0,0]
	v_cvt_scalef32_pk_bf16_fp4 v52, v81, 1.0 op_sel:[0,1,0]
	v_cvt_scalef32_pk_bf16_fp4 v56, v81, 1.0 op_sel:[1,1,0]
	s_mov_b32 s27, s86
	v_dot2_f32_bf16 v54, v48, v14, v54
	v_dot2_f32_bf16 v46, v50, v12, v46
	s_lshl_b64 s[26:27], s[26:27], 10
	v_dot2_f32_bf16 v54, v52, v18, v54
	v_dot2_f32_bf16 v46, v56, v16, v46
	v_cvt_scalef32_pk_bf16_fp4 v48, v82, 1.0
	v_cvt_scalef32_pk_bf16_fp4 v50, v82, 1.0 op_sel:[1,0,0]
	v_cvt_scalef32_pk_bf16_fp4 v52, v82, 1.0 op_sel:[0,1,0]
	v_cvt_scalef32_pk_bf16_fp4 v56, v82, 1.0 op_sel:[1,1,0]
	s_add_u32 s26, s13, s26
	v_dot2_f32_bf16 v54, v48, v22, v54
	v_dot2_f32_bf16 v46, v50, v20, v46
	s_addc_u32 s27, s12, s27
	v_dot2_f32_bf16 v54, v52, v26, v54
	v_dot2_f32_bf16 v46, v56, v24, v46
	v_cvt_scalef32_pk_bf16_fp4 v48, v83, 1.0
	v_cvt_scalef32_pk_bf16_fp4 v50, v83, 1.0 op_sel:[1,0,0]
	v_cvt_scalef32_pk_bf16_fp4 v52, v83, 1.0 op_sel:[0,1,0]
	v_cvt_scalef32_pk_bf16_fp4 v56, v83, 1.0 op_sel:[1,1,0]
	s_nop 0
	v_dot2_f32_bf16 v54, v48, v30, v54
	v_dot2_f32_bf16 v46, v50, v28, v46
	s_nop 0
	v_dot2_f32_bf16 v54, v52, v36, v54
	v_dot2_f32_bf16 v46, v56, v34, v46
	s_nop 0
	s_nop 2
	v_add_f32_e32 v45, v54, v46
	global_load_dwordx4 v[80:83], v32, s[26:27]
	s_waitcnt vmcnt(15)
	v_cvt_scalef32_pk_bf16_fp4 v46, v84, 1.0
	v_cvt_scalef32_pk_bf16_fp4 v48, v84, 1.0 op_sel:[1,0,0]
	v_cvt_scalef32_pk_bf16_fp4 v50, v84, 1.0 op_sel:[0,1,0]
	v_cvt_scalef32_pk_bf16_fp4 v52, v84, 1.0 op_sel:[1,1,0]
	v_dot2_f32_bf16 v54, v46, v6, 0
	v_dot2_f32_bf16 v46, v48, v4, 0
	v_dot2_f32_bf16 v54, v50, v10, v54
	v_readlane_b32 s26, v2, 5
	v_dot2_f32_bf16 v46, v52, v8, v46
	v_cvt_scalef32_pk_bf16_fp4 v48, v85, 1.0
	v_cvt_scalef32_pk_bf16_fp4 v50, v85, 1.0 op_sel:[1,0,0]
	v_cvt_scalef32_pk_bf16_fp4 v52, v85, 1.0 op_sel:[0,1,0]
	v_cvt_scalef32_pk_bf16_fp4 v56, v85, 1.0 op_sel:[1,1,0]
	s_lshr_b32 s26, s26, 7
	v_dot2_f32_bf16 v54, v48, v14, v54
	v_dot2_f32_bf16 v46, v50, v12, v46
	s_mov_b32 s27, s86
	v_dot2_f32_bf16 v54, v52, v18, v54
	v_dot2_f32_bf16 v46, v56, v16, v46
	v_cvt_scalef32_pk_bf16_fp4 v48, v86, 1.0
	v_cvt_scalef32_pk_bf16_fp4 v50, v86, 1.0 op_sel:[1,0,0]
	v_cvt_scalef32_pk_bf16_fp4 v52, v86, 1.0 op_sel:[0,1,0]
	v_cvt_scalef32_pk_bf16_fp4 v56, v86, 1.0 op_sel:[1,1,0]
	s_lshl_b64 s[26:27], s[26:27], 10
	v_dot2_f32_bf16 v54, v48, v22, v54
	v_dot2_f32_bf16 v46, v50, v20, v46
	s_add_u32 s26, s13, s26
	v_dot2_f32_bf16 v54, v52, v26, v54
	v_dot2_f32_bf16 v46, v56, v24, v46
	v_cvt_scalef32_pk_bf16_fp4 v48, v87, 1.0
	v_cvt_scalef32_pk_bf16_fp4 v50, v87, 1.0 op_sel:[1,0,0]
	v_cvt_scalef32_pk_bf16_fp4 v52, v87, 1.0 op_sel:[0,1,0]
	v_cvt_scalef32_pk_bf16_fp4 v56, v87, 1.0 op_sel:[1,1,0]
	s_addc_u32 s27, s12, s27
	v_dot2_f32_bf16 v54, v48, v30, v54
	v_dot2_f32_bf16 v46, v50, v28, v46
	s_nop 0
	v_dot2_f32_bf16 v54, v52, v36, v54
	v_dot2_f32_bf16 v46, v56, v34, v46
	s_nop 2
	v_add_f32_e32 v46, v54, v46
	global_load_dwordx4 v[84:87], v32, s[26:27]
	s_waitcnt vmcnt(15)
; #define P4_FOR16(M) M(0) M(1) M(2) M(3) M(4) M(5) M(6) M(7) M(8) M(9) M(10) M(11) M(12) M(13) M(14) M(15)
; #define P4_U(i) { P4_DOT(b##i, part[i]); const int nk_ = __builtin_amdgcn_readlane(ksel, nb + i); P4_LOAD(b##i, Ug, nk_); }
; #define P4_U(i) { P4_DOT(b##i, part[i]); const int nk_ = __builtin_amdgcn_readlane(kn, i); P4_LOAD(b##i, nbase, nk_); }
; __device__ __forceinline__ void peer_gather_f4p(const float* X, const int* __restrict__ IDX, const float* __restrict__ G, ...
;     ...
;             P4_FOR16(P4_U)
	v_cvt_scalef32_pk_bf16_fp4 v48, v88, 1.0
	v_cvt_scalef32_pk_bf16_fp4 v50, v88, 1.0 op_sel:[1,0,0]
	v_cvt_scalef32_pk_bf16_fp4 v52, v88, 1.0 op_sel:[0,1,0]
	v_cvt_scalef32_pk_bf16_fp4 v54, v88, 1.0 op_sel:[1,1,0]
	v_readlane_b32 s26, v2, 6
	v_dot2_f32_bf16 v56, v48, v6, 0
	v_dot2_f32_bf16 v48, v50, v4, 0
	v_dot2_f32_bf16 v56, v52, v10, v56
	s_lshr_b32 s26, s26, 7
	v_dot2_f32_bf16 v48, v54, v8, v48
	v_cvt_scalef32_pk_bf16_fp4 v50, v89, 1.0
	v_cvt_scalef32_pk_bf16_fp4 v52, v89, 1.0 op_sel:[1,0,0]
	v_cvt_scalef32_pk_bf16_fp4 v54, v89, 1.0 op_sel:[0,1,0]
	v_cvt_scalef32_pk_bf16_fp4 v58, v89, 1.0 op_sel:[1,1,0]
	s_mov_b32 s27, s86
	v_dot2_f32_bf16 v56, v50, v14, v56
	v_dot2_f32_bf16 v48, v52, v12, v48
	s_lshl_b64 s[26:27], s[26:27], 10
	v_dot2_f32_bf16 v56, v54, v18, v56
	v_dot2_f32_bf16 v48, v58, v16, v48
	v_cvt_scalef32_pk_bf16_fp4 v50, v90, 1.0
	v_cvt_scalef32_pk_bf16_fp4 v52, v90, 1.0 op_sel:[1,0,0]
	v_cvt_scalef32_pk_bf16_fp4 v54, v90, 1.0 op_sel:[0,1,0]
	v_cvt_scalef32_pk_bf16_fp4 v58, v90, 1.0 op_sel:[1,1,0]
	s_add_u32 s26, s13, s26
	v_dot2_f32_bf16 v56, v50, v22, v56
	v_dot2_f32_bf16 v48, v52, v20, v48
	s_addc_u32 s27, s12, s27
	v_dot2_f32_bf16 v56, v54, v26, v56
	v_dot2_f32_bf16 v48, v58, v24, v48
	v_cvt_scalef32_pk_bf16_fp4 v50, v91, 1.0
	v_cvt_scalef32_pk_bf16_fp4 v52, v91, 1.0 op_sel:[1,0,0]
	v_cvt_scalef32_pk_bf16_fp4 v54, v91, 1.0 op_sel:[0,1,0]
	v_cvt_scalef32_pk_bf16_fp4 v58, v91, 1.0 op_sel:[1,1,0]
	s_nop 0
	v_dot2_f32_bf16 v56, v50, v30, v56
	v_dot2_f32_bf16 v48, v52, v28, v48
	s_nop 0
	v_dot2_f32_bf16 v56, v54, v36, v56
	v_dot2_f32_bf16 v48, v58, v34, v48
	s_nop 0
	s_nop 2
	v_add_f32_e32 v47, v56, v48
	global_load_dwordx4 v[88:91], v32, s[26:27]
	s_waitcnt vmcnt(15)
	v_cvt_scalef32_pk_bf16_fp4 v48, v92, 1.0
	v_cvt_scalef32_pk_bf16_fp4 v50, v92, 1.0 op_sel:[1,0,0]
	v_cvt_scalef32_pk_bf16_fp4 v52, v92, 1.0 op_sel:[0,1,0]
	v_cvt_scalef32_pk_bf16_fp4 v54, v92, 1.0 op_sel:[1,1,0]
	v_dot2_f32_bf16 v56, v48, v6, 0
	v_dot2_f32_bf16 v48, v50, v4, 0
	v_dot2_f32_bf16 v56, v52, v10, v56
	v_readlane_b32 s26, v2, 7
	v_dot2_f32_bf16 v48, v54, v8, v48
	v_cvt_scalef32_pk_bf16_fp4 v50, v93, 1.0
	v_cvt_scalef32_pk_bf16_fp4 v52, v93, 1.0 op_sel:[1,0,0]
	v_cvt_scalef32_pk_bf16_fp4 v54, v93, 1.0 op_sel:[0,1,0]
	v_cvt_scalef32_pk_bf16_fp4 v58, v93, 1.0 op_sel:[1,1,0]
	s_lshr_b32 s26, s26, 7
	v_dot2_f32_bf16 v56, v50, v14, v56
	v_dot2_f32_bf16 v48, v52, v12, v48
	s_mov_b32 s27, s86
	v_dot2_f32_bf16 v56, v54, v18, v56
	v_dot2_f32_bf16 v48, v58, v16, v48
	v_cvt_scalef32_pk_bf16_fp4 v50, v94, 1.0
	v_cvt_scalef32_pk_bf16_fp4 v52, v94, 1.0 op_sel:[1,0,0]
	v_cvt_scalef32_pk_bf16_fp4 v54, v94, 1.0 op_sel:[0,1,0]
	v_cvt_scalef32_pk_bf16_fp4 v58, v94, 1.0 op_sel:[1,1,0]
	s_lshl_b64 s[26:27], s[26:27], 10
	v_dot2_f32_bf16 v56, v50, v22, v56
	v_dot2_f32_bf16 v48, v52, v20, v48
	s_add_u32 s26, s13, s26
	v_dot2_f32_bf16 v56, v54, v26, v56
	v_dot2_f32_bf16 v48, v58, v24, v48
	v_cvt_scalef32_pk_bf16_fp4 v50, v95, 1.0
	v_cvt_scalef32_pk_bf16_fp4 v52, v95, 1.0 op_sel:[1,0,0]
	v_cvt_scalef32_pk_bf16_fp4 v54, v95, 1.0 op_sel:[0,1,0]
	v_cvt_scalef32_pk_bf16_fp4 v58, v95, 1.0 op_sel:[1,1,0]
	s_addc_u32 s27, s12, s27
	v_dot2_f32_bf16 v56, v50, v30, v56
	v_dot2_f32_bf16 v48, v52, v28, v48
	s_nop 0
	v_dot2_f32_bf16 v56, v54, v36, v56
	v_dot2_f32_bf16 v48, v58, v34, v48
	s_nop 2
	v_add_f32_e32 v48, v56, v48
	global_load_dwordx4 v[92:95], v32, s[26:27]
	s_waitcnt vmcnt(15)
	v_cvt_scalef32_pk_bf16_fp4 v50, v96, 1.0
	v_cvt_scalef32_pk_bf16_fp4 v52, v96, 1.0 op_sel:[1,0,0]
	v_cvt_scalef32_pk_bf16_fp4 v54, v96, 1.0 op_sel:[0,1,0]
	v_cvt_scalef32_pk_bf16_fp4 v56, v96, 1.0 op_sel:[1,1,0]
	v_readlane_b32 s26, v2, 8
	v_dot2_f32_bf16 v58, v50, v6, 0
	v_dot2_f32_bf16 v50, v52, v4, 0
	v_dot2_f32_bf16 v58, v54, v10, v58
	s_lshr_b32 s26, s26, 7
	v_dot2_f32_bf16 v50, v56, v8, v50
	v_cvt_scalef32_pk_bf16_fp4 v52, v97, 1.0
	v_cvt_scalef32_pk_bf16_fp4 v54, v97, 1.0 op_sel:[1,0,0]
	v_cvt_scalef32_pk_bf16_fp4 v56, v97, 1.0 op_sel:[0,1,0]
	v_cvt_scalef32_pk_bf16_fp4 v60, v97, 1.0 op_sel:[1,1,0]
	s_mov_b32 s27, s86
	v_dot2_f32_bf16 v58, v52, v14, v58
	v_dot2_f32_bf16 v50, v54, v12, v50
	s_lshl_b64 s[26:27], s[26:27], 10
	v_dot2_f32_bf16 v58, v56, v18, v58
	v_dot2_f32_bf16 v50, v60, v16, v50
	v_cvt_scalef32_pk_bf16_fp4 v52, v98, 1.0
	v_cvt_scalef32_pk_bf16_fp4 v54, v98, 1.0 op_sel:[1,0,0]
	v_cvt_scalef32_pk_bf16_fp4 v56, v98, 1.0 op_sel:[0,1,0]
	v_cvt_scalef32_pk_bf16_fp4 v60, v98, 1.0 op_sel:[1,1,0]
	s_add_u32 s26, s13, s26
	v_dot2_f32_bf16 v58, v52, v22, v58
	v_dot2_f32_bf16 v50, v54, v20, v50
	s_addc_u32 s27, s12, s27
	v_dot2_f32_bf16 v58, v56, v26, v58
	v_dot2_f32_bf16 v50, v60, v24, v50
	v_cvt_scalef32_pk_bf16_fp4 v52, v99, 1.0
	v_cvt_scalef32_pk_bf16_fp4 v54, v99, 1.0 op_sel:[1,0,0]
	v_cvt_scalef32_pk_bf16_fp4 v56, v99, 1.0 op_sel:[0,1,0]
	v_cvt_scalef32_pk_bf16_fp4 v60, v99, 1.0 op_sel:[1,1,0]
	s_nop 0
	v_dot2_f32_bf16 v58, v52, v30, v58
	v_dot2_f32_bf16 v50, v54, v28, v50
	s_nop 0
	v_dot2_f32_bf16 v58, v56, v36, v58
	v_dot2_f32_bf16 v50, v60, v34, v50
	s_nop 0
	s_nop 2
	v_add_f32_e32 v49, v58, v50
	global_load_dwordx4 v[96:99], v32, s[26:27]
	s_waitcnt vmcnt(15)
; #define P4_FOR16(M) M(0) M(1) M(2) M(3) M(4) M(5) M(6) M(7) M(8) M(9) M(10) M(11) M(12) M(13) M(14) M(15)
; #define P4_U(i) { P4_DOT(b##i, part[i]); const int nk_ = __builtin_amdgcn_readlane(ksel, nb + i); P4_LOAD(b##i, Ug, nk_); }
; #define P4_U(i) { P4_DOT(b##i, part[i]); const int nk_ = __builtin_amdgcn_readlane(kn, i); P4_LOAD(b##i, nbase, nk_); }
; __device__ __forceinline__ void peer_gather_f4p(const float* X, const int* __restrict__ IDX, const float* __restrict__ G, ...
;     ...
;             P4_FOR16(P4_U)
	v_cvt_scalef32_pk_bf16_fp4 v50, v104, 1.0
	v_cvt_scalef32_pk_bf16_fp4 v52, v104, 1.0 op_sel:[1,0,0]
	v_cvt_scalef32_pk_bf16_fp4 v54, v104, 1.0 op_sel:[0,1,0]
	v_cvt_scalef32_pk_bf16_fp4 v56, v104, 1.0 op_sel:[1,1,0]
	v_dot2_f32_bf16 v58, v50, v6, 0
	v_dot2_f32_bf16 v50, v52, v4, 0
	v_dot2_f32_bf16 v58, v54, v10, v58
	v_readlane_b32 s26, v2, 9
	v_dot2_f32_bf16 v50, v56, v8, v50
	v_cvt_scalef32_pk_bf16_fp4 v52, v105, 1.0
	v_cvt_scalef32_pk_bf16_fp4 v54, v105, 1.0 op_sel:[1,0,0]
	v_cvt_scalef32_pk_bf16_fp4 v56, v105, 1.0 op_sel:[0,1,0]
	v_cvt_scalef32_pk_bf16_fp4 v60, v105, 1.0 op_sel:[1,1,0]
	s_lshr_b32 s26, s26, 7
	v_dot2_f32_bf16 v58, v52, v14, v58
	v_dot2_f32_bf16 v50, v54, v12, v50
	s_mov_b32 s27, s86
	v_dot2_f32_bf16 v58, v56, v18, v58
	v_dot2_f32_bf16 v50, v60, v16, v50
	v_cvt_scalef32_pk_bf16_fp4 v52, v106, 1.0
	v_cvt_scalef32_pk_bf16_fp4 v54, v106, 1.0 op_sel:[1,0,0]
	v_cvt_scalef32_pk_bf16_fp4 v56, v106, 1.0 op_sel:[0,1,0]
	v_cvt_scalef32_pk_bf16_fp4 v60, v106, 1.0 op_sel:[1,1,0]
	s_lshl_b64 s[26:27], s[26:27], 10
	v_dot2_f32_bf16 v58, v52, v22, v58
	v_dot2_f32_bf16 v50, v54, v20, v50
	s_add_u32 s26, s13, s26
	v_dot2_f32_bf16 v58, v56, v26, v58
	v_dot2_f32_bf16 v50, v60, v24, v50
	v_cvt_scalef32_pk_bf16_fp4 v52, v107, 1.0
	v_cvt_scalef32_pk_bf16_fp4 v54, v107, 1.0 op_sel:[1,0,0]
	v_cvt_scalef32_pk_bf16_fp4 v56, v107, 1.0 op_sel:[0,1,0]
	v_cvt_scalef32_pk_bf16_fp4 v60, v107, 1.0 op_sel:[1,1,0]
	s_addc_u32 s27, s12, s27
	v_dot2_f32_bf16 v58, v52, v30, v58
	v_dot2_f32_bf16 v50, v54, v28, v50
	s_nop 0
	v_dot2_f32_bf16 v58, v56, v36, v58
	v_dot2_f32_bf16 v50, v60, v34, v50
	s_nop 2
	v_add_f32_e32 v50, v58, v50
	global_load_dwordx4 v[104:107], v32, s[26:27]
	s_waitcnt vmcnt(15)
	v_cvt_scalef32_pk_bf16_fp4 v52, v108, 1.0
	v_cvt_scalef32_pk_bf16_fp4 v54, v108, 1.0 op_sel:[1,0,0]
	v_cvt_scalef32_pk_bf16_fp4 v56, v108, 1.0 op_sel:[0,1,0]
	v_cvt_scalef32_pk_bf16_fp4 v58, v108, 1.0 op_sel:[1,1,0]
	v_readlane_b32 s26, v2, 10
	v_dot2_f32_bf16 v60, v52, v6, 0
	v_dot2_f32_bf16 v52, v54, v4, 0
	v_dot2_f32_bf16 v60, v56, v10, v60
	s_lshr_b32 s26, s26, 7
	v_dot2_f32_bf16 v52, v58, v8, v52
	v_cvt_scalef32_pk_bf16_fp4 v54, v109, 1.0
	v_cvt_scalef32_pk_bf16_fp4 v56, v109, 1.0 op_sel:[1,0,0]
	v_cvt_scalef32_pk_bf16_fp4 v58, v109, 1.0 op_sel:[0,1,0]
	v_cvt_scalef32_pk_bf16_fp4 v62, v109, 1.0 op_sel:[1,1,0]
	s_mov_b32 s27, s86
	v_dot2_f32_bf16 v60, v54, v14, v60
	v_dot2_f32_bf16 v52, v56, v12, v52
	s_lshl_b64 s[26:27], s[26:27], 10
	v_dot2_f32_bf16 v60, v58, v18, v60
	v_dot2_f32_bf16 v52, v62, v16, v52
	v_cvt_scalef32_pk_bf16_fp4 v54, v110, 1.0
	v_cvt_scalef32_pk_bf16_fp4 v56, v110, 1.0 op_sel:[1,0,0]
	v_cvt_scalef32_pk_bf16_fp4 v58, v110, 1.0 op_sel:[0,1,0]
	v_cvt_scalef32_pk_bf16_fp4 v62, v110, 1.0 op_sel:[1,1,0]
	s_add_u32 s26, s13, s26
	v_dot2_f32_bf16 v60, v54, v22, v60
	v_dot2_f32_bf16 v52, v56, v20, v52
	s_addc_u32 s27, s12, s27
	v_dot2_f32_bf16 v60, v58, v26, v60
	v_dot2_f32_bf16 v52, v62, v24, v52
	v_cvt_scalef32_pk_bf16_fp4 v54, v111, 1.0
	v_cvt_scalef32_pk_bf16_fp4 v56, v111, 1.0 op_sel:[1,0,0]
	v_cvt_scalef32_pk_bf16_fp4 v58, v111, 1.0 op_sel:[0,1,0]
	v_cvt_scalef32_pk_bf16_fp4 v62, v111, 1.0 op_sel:[1,1,0]
	s_nop 0
	v_dot2_f32_bf16 v60, v54, v30, v60
	v_dot2_f32_bf16 v52, v56, v28, v52
	s_nop 0
	v_dot2_f32_bf16 v60, v58, v36, v60
	v_dot2_f32_bf16 v52, v62, v34, v52
	s_nop 0
	s_nop 2
	v_add_f32_e32 v51, v60, v52
	global_load_dwordx4 v[108:111], v32, s[26:27]
	s_waitcnt vmcnt(15)
	v_cvt_scalef32_pk_bf16_fp4 v52, v112, 1.0
	v_cvt_scalef32_pk_bf16_fp4 v54, v112, 1.0 op_sel:[1,0,0]
	v_cvt_scalef32_pk_bf16_fp4 v56, v112, 1.0 op_sel:[0,1,0]
	v_cvt_scalef32_pk_bf16_fp4 v58, v112, 1.0 op_sel:[1,1,0]
	v_dot2_f32_bf16 v60, v52, v6, 0
	v_dot2_f32_bf16 v52, v54, v4, 0
	v_dot2_f32_bf16 v60, v56, v10, v60
	v_readlane_b32 s26, v2, 11
	v_dot2_f32_bf16 v52, v58, v8, v52
	v_cvt_scalef32_pk_bf16_fp4 v54, v113, 1.0
	v_cvt_scalef32_pk_bf16_fp4 v56, v113, 1.0 op_sel:[1,0,0]
	v_cvt_scalef32_pk_bf16_fp4 v58, v113, 1.0 op_sel:[0,1,0]
	v_cvt_scalef32_pk_bf16_fp4 v62, v113, 1.0 op_sel:[1,1,0]
	s_lshr_b32 s26, s26, 7
	v_dot2_f32_bf16 v60, v54, v14, v60
	v_dot2_f32_bf16 v52, v56, v12, v52
	s_mov_b32 s27, s86
	v_dot2_f32_bf16 v60, v58, v18, v60
	v_dot2_f32_bf16 v52, v62, v16, v52
	v_cvt_scalef32_pk_bf16_fp4 v54, v114, 1.0
	v_cvt_scalef32_pk_bf16_fp4 v56, v114, 1.0 op_sel:[1,0,0]
	v_cvt_scalef32_pk_bf16_fp4 v58, v114, 1.0 op_sel:[0,1,0]
	v_cvt_scalef32_pk_bf16_fp4 v62, v114, 1.0 op_sel:[1,1,0]
	s_lshl_b64 s[26:27], s[26:27], 10
	v_dot2_f32_bf16 v60, v54, v22, v60
	v_dot2_f32_bf16 v52, v56, v20, v52
	s_add_u32 s26, s13, s26
	v_dot2_f32_bf16 v60, v58, v26, v60
	v_dot2_f32_bf16 v52, v62, v24, v52
	v_cvt_scalef32_pk_bf16_fp4 v54, v115, 1.0
	v_cvt_scalef32_pk_bf16_fp4 v56, v115, 1.0 op_sel:[1,0,0]
	v_cvt_scalef32_pk_bf16_fp4 v58, v115, 1.0 op_sel:[0,1,0]
	v_cvt_scalef32_pk_bf16_fp4 v62, v115, 1.0 op_sel:[1,1,0]
	s_addc_u32 s27, s12, s27
	v_dot2_f32_bf16 v60, v54, v30, v60
	v_dot2_f32_bf16 v52, v56, v28, v52
	s_nop 0
	v_dot2_f32_bf16 v60, v58, v36, v60
	v_dot2_f32_bf16 v52, v62, v34, v52
	s_nop 0
	s_nop 2
	v_add_f32_e32 v100, v60, v52
	global_load_dwordx4 v[112:115], v32, s[26:27]
	s_waitcnt vmcnt(15)
; #define P4_FOR16(M) M(0) M(1) M(2) M(3) M(4) M(5) M(6) M(7) M(8) M(9) M(10) M(11) M(12) M(13) M(14) M(15)
; #define P4_U(i) { P4_DOT(b##i, part[i]); const int nk_ = __builtin_amdgcn_readlane(ksel, nb + i); P4_LOAD(b##i, Ug, nk_); }
; #define P4_U(i) { P4_DOT(b##i, part[i]); const int nk_ = __builtin_amdgcn_readlane(kn, i); P4_LOAD(b##i, nbase, nk_); }
; __device__ __forceinline__ void peer_gather_f4p(const float* X, const int* __restrict__ IDX, const float* __restrict__ G, ...
;     ...
;             P4_FOR16(P4_U)
	v_cvt_scalef32_pk_bf16_fp4 v52, v116, 1.0
	v_cvt_scalef32_pk_bf16_fp4 v54, v116, 1.0 op_sel:[1,0,0]
	v_cvt_scalef32_pk_bf16_fp4 v56, v116, 1.0 op_sel:[0,1,0]
	v_cvt_scalef32_pk_bf16_fp4 v58, v116, 1.0 op_sel:[1,1,0]
	v_dot2_f32_bf16 v60, v52, v6, 0
	v_dot2_f32_bf16 v52, v54, v4, 0
	v_dot2_f32_bf16 v60, v56, v10, v60
	v_readlane_b32 s26, v2, 12
	v_dot2_f32_bf16 v52, v58, v8, v52
	v_cvt_scalef32_pk_bf16_fp4 v54, v117, 1.0
	v_cvt_scalef32_pk_bf16_fp4 v56, v117, 1.0 op_sel:[1,0,0]
	v_cvt_scalef32_pk_bf16_fp4 v58, v117, 1.0 op_sel:[0,1,0]
	v_cvt_scalef32_pk_bf16_fp4 v62, v117, 1.0 op_sel:[1,1,0]
	s_lshr_b32 s26, s26, 7
	v_dot2_f32_bf16 v60, v54, v14, v60
	v_dot2_f32_bf16 v52, v56, v12, v52
	s_mov_b32 s27, s86
	v_dot2_f32_bf16 v60, v58, v18, v60
	v_dot2_f32_bf16 v52, v62, v16, v52
	v_cvt_scalef32_pk_bf16_fp4 v54, v118, 1.0
	v_cvt_scalef32_pk_bf16_fp4 v56, v118, 1.0 op_sel:[1,0,0]
	v_cvt_scalef32_pk_bf16_fp4 v58, v118, 1.0 op_sel:[0,1,0]
	v_cvt_scalef32_pk_bf16_fp4 v62, v118, 1.0 op_sel:[1,1,0]
	s_lshl_b64 s[26:27], s[26:27], 10
	v_dot2_f32_bf16 v60, v54, v22, v60
	v_dot2_f32_bf16 v52, v56, v20, v52
	s_add_u32 s26, s13, s26
	v_dot2_f32_bf16 v60, v58, v26, v60
	v_dot2_f32_bf16 v52, v62, v24, v52
	v_cvt_scalef32_pk_bf16_fp4 v54, v119, 1.0
	v_cvt_scalef32_pk_bf16_fp4 v56, v119, 1.0 op_sel:[1,0,0]
	v_cvt_scalef32_pk_bf16_fp4 v58, v119, 1.0 op_sel:[0,1,0]
	v_cvt_scalef32_pk_bf16_fp4 v62, v119, 1.0 op_sel:[1,1,0]
	s_addc_u32 s27, s12, s27
	v_dot2_f32_bf16 v60, v54, v30, v60
	v_dot2_f32_bf16 v52, v56, v28, v52
	s_nop 0
	v_dot2_f32_bf16 v60, v58, v36, v60
	v_dot2_f32_bf16 v52, v62, v34, v52
	s_nop 0
	s_nop 2
	v_add_f32_e32 v101, v60, v52
	global_load_dwordx4 v[116:119], v32, s[26:27]
	s_waitcnt vmcnt(15)
	v_cvt_scalef32_pk_bf16_fp4 v52, v120, 1.0
	v_cvt_scalef32_pk_bf16_fp4 v54, v120, 1.0 op_sel:[1,0,0]
	v_cvt_scalef32_pk_bf16_fp4 v56, v120, 1.0 op_sel:[0,1,0]
	v_cvt_scalef32_pk_bf16_fp4 v58, v120, 1.0 op_sel:[1,1,0]
	v_dot2_f32_bf16 v60, v52, v6, 0
	v_dot2_f32_bf16 v52, v54, v4, 0
	v_dot2_f32_bf16 v60, v56, v10, v60
	v_readlane_b32 s26, v2, 13
	v_dot2_f32_bf16 v52, v58, v8, v52
	v_cvt_scalef32_pk_bf16_fp4 v54, v121, 1.0
	v_cvt_scalef32_pk_bf16_fp4 v56, v121, 1.0 op_sel:[1,0,0]
	v_cvt_scalef32_pk_bf16_fp4 v58, v121, 1.0 op_sel:[0,1,0]
	v_cvt_scalef32_pk_bf16_fp4 v62, v121, 1.0 op_sel:[1,1,0]
	s_lshr_b32 s26, s26, 7
	v_dot2_f32_bf16 v60, v54, v14, v60
	v_dot2_f32_bf16 v52, v56, v12, v52
	s_mov_b32 s27, s86
	v_dot2_f32_bf16 v60, v58, v18, v60
	v_dot2_f32_bf16 v52, v62, v16, v52
	v_cvt_scalef32_pk_bf16_fp4 v54, v122, 1.0
	v_cvt_scalef32_pk_bf16_fp4 v56, v122, 1.0 op_sel:[1,0,0]
	v_cvt_scalef32_pk_bf16_fp4 v58, v122, 1.0 op_sel:[0,1,0]
	v_cvt_scalef32_pk_bf16_fp4 v62, v122, 1.0 op_sel:[1,1,0]
	s_lshl_b64 s[26:27], s[26:27], 10
	v_dot2_f32_bf16 v60, v54, v22, v60
	v_dot2_f32_bf16 v52, v56, v20, v52
	s_add_u32 s26, s13, s26
	v_dot2_f32_bf16 v60, v58, v26, v60
	v_dot2_f32_bf16 v52, v62, v24, v52
	v_cvt_scalef32_pk_bf16_fp4 v54, v123, 1.0
	v_cvt_scalef32_pk_bf16_fp4 v56, v123, 1.0 op_sel:[1,0,0]
	v_cvt_scalef32_pk_bf16_fp4 v58, v123, 1.0 op_sel:[0,1,0]
	v_cvt_scalef32_pk_bf16_fp4 v62, v123, 1.0 op_sel:[1,1,0]
	s_addc_u32 s27, s12, s27
	v_dot2_f32_bf16 v60, v54, v30, v60
	v_dot2_f32_bf16 v52, v56, v28, v52
	s_nop 0
	v_dot2_f32_bf16 v60, v58, v36, v60
	v_dot2_f32_bf16 v52, v62, v34, v52
	s_nop 0
	s_nop 2
	v_add_f32_e32 v102, v60, v52
	global_load_dwordx4 v[120:123], v32, s[26:27]
	s_waitcnt vmcnt(15)
	v_cvt_scalef32_pk_bf16_fp4 v52, v124, 1.0
	v_cvt_scalef32_pk_bf16_fp4 v54, v124, 1.0 op_sel:[1,0,0]
	v_cvt_scalef32_pk_bf16_fp4 v56, v124, 1.0 op_sel:[0,1,0]
	v_cvt_scalef32_pk_bf16_fp4 v58, v124, 1.0 op_sel:[1,1,0]
	v_dot2_f32_bf16 v60, v52, v6, 0
	v_dot2_f32_bf16 v52, v54, v4, 0
	v_dot2_f32_bf16 v60, v56, v10, v60
	v_readlane_b32 s26, v2, 14
	v_dot2_f32_bf16 v52, v58, v8, v52
	v_cvt_scalef32_pk_bf16_fp4 v54, v125, 1.0
	v_cvt_scalef32_pk_bf16_fp4 v56, v125, 1.0 op_sel:[1,0,0]
	v_cvt_scalef32_pk_bf16_fp4 v58, v125, 1.0 op_sel:[0,1,0]
	v_cvt_scalef32_pk_bf16_fp4 v62, v125, 1.0 op_sel:[1,1,0]
	s_lshr_b32 s26, s26, 7
	v_dot2_f32_bf16 v60, v54, v14, v60
	v_dot2_f32_bf16 v52, v56, v12, v52
	s_mov_b32 s27, s86
	v_dot2_f32_bf16 v60, v58, v18, v60
	v_dot2_f32_bf16 v52, v62, v16, v52
	v_cvt_scalef32_pk_bf16_fp4 v54, v126, 1.0
	v_cvt_scalef32_pk_bf16_fp4 v56, v126, 1.0 op_sel:[1,0,0]
	v_cvt_scalef32_pk_bf16_fp4 v58, v126, 1.0 op_sel:[0,1,0]
	v_cvt_scalef32_pk_bf16_fp4 v62, v126, 1.0 op_sel:[1,1,0]
	s_lshl_b64 s[26:27], s[26:27], 10
	v_dot2_f32_bf16 v60, v54, v22, v60
	v_dot2_f32_bf16 v52, v56, v20, v52
	s_add_u32 s26, s13, s26
	v_dot2_f32_bf16 v60, v58, v26, v60
	v_dot2_f32_bf16 v52, v62, v24, v52
	v_cvt_scalef32_pk_bf16_fp4 v54, v127, 1.0
	v_cvt_scalef32_pk_bf16_fp4 v56, v127, 1.0 op_sel:[1,0,0]
	v_cvt_scalef32_pk_bf16_fp4 v58, v127, 1.0 op_sel:[0,1,0]
	v_cvt_scalef32_pk_bf16_fp4 v62, v127, 1.0 op_sel:[1,1,0]
	s_addc_u32 s27, s12, s27
	v_dot2_f32_bf16 v60, v54, v30, v60
	v_dot2_f32_bf16 v52, v56, v28, v52
	s_nop 0
	v_dot2_f32_bf16 v60, v58, v36, v60
	v_dot2_f32_bf16 v52, v62, v34, v52
	s_nop 0
	s_nop 2
	v_add_f32_e32 v62, v60, v52
	global_load_dwordx4 v[124:127], v32, s[26:27]
	s_waitcnt vmcnt(15)
; __device__ __forceinline__ float gelu_tanh(float h) {
;     return 0.5f * h * (1.f + tanhf(0.7978845608028654f * (h + 0.044715f * h * h * h)));
; }
	v_cvt_scalef32_pk_bf16_fp4 v52, v128, 1.0
	v_cvt_scalef32_pk_bf16_fp4 v54, v128, 1.0 op_sel:[1,0,0]
	v_cvt_scalef32_pk_bf16_fp4 v56, v128, 1.0 op_sel:[0,1,0]
	v_cvt_scalef32_pk_bf16_fp4 v58, v128, 1.0 op_sel:[1,1,0]
	v_readlane_b32 s26, v2, 15
	v_dot2_f32_bf16 v60, v52, v6, 0
	v_dot2c_f32_bf16_e32 v38, v54, v4
	s_lshr_b32 s26, s26, 7
	v_dot2_f32_bf16 v60, v56, v10, v60
	v_dot2c_f32_bf16_e32 v38, v58, v8
	v_cvt_scalef32_pk_bf16_fp4 v4, v129, 1.0
	v_cvt_scalef32_pk_bf16_fp4 v6, v129, 1.0 op_sel:[1,0,0]
	v_cvt_scalef32_pk_bf16_fp4 v8, v129, 1.0 op_sel:[0,1,0]
	v_cvt_scalef32_pk_bf16_fp4 v10, v129, 1.0 op_sel:[1,1,0]
	s_mov_b32 s27, s86
	v_dot2_f32_bf16 v60, v4, v14, v60
	v_dot2c_f32_bf16_e32 v38, v6, v12
	s_lshl_b64 s[26:27], s[26:27], 10
	v_dot2_f32_bf16 v60, v8, v18, v60
	v_dot2c_f32_bf16_e32 v38, v10, v16
	v_cvt_scalef32_pk_bf16_fp4 v4, v130, 1.0
	v_cvt_scalef32_pk_bf16_fp4 v6, v130, 1.0 op_sel:[1,0,0]
	v_cvt_scalef32_pk_bf16_fp4 v8, v130, 1.0 op_sel:[0,1,0]
	v_cvt_scalef32_pk_bf16_fp4 v10, v130, 1.0 op_sel:[1,1,0]
	s_add_u32 s26, s13, s26
	v_dot2_f32_bf16 v60, v4, v22, v60
	v_dot2c_f32_bf16_e32 v38, v6, v20
	s_addc_u32 s27, s12, s27
	v_dot2_f32_bf16 v60, v8, v26, v60
	v_dot2c_f32_bf16_e32 v38, v10, v24
	v_cvt_scalef32_pk_bf16_fp4 v4, v131, 1.0
	v_cvt_scalef32_pk_bf16_fp4 v6, v131, 1.0 op_sel:[1,0,0]
	v_cvt_scalef32_pk_bf16_fp4 v8, v131, 1.0 op_sel:[0,1,0]
	v_cvt_scalef32_pk_bf16_fp4 v10, v131, 1.0 op_sel:[1,1,0]
	v_cndmask_b32_e64 v2, v49, v41, s[48:49]
	v_dot2_f32_bf16 v60, v4, v30, v60
	v_dot2c_f32_bf16_e32 v38, v6, v28
	v_cndmask_b32_e64 v7, v43, v51, s[48:49]
	v_dot2_f32_bf16 v60, v8, v36, v60
	v_dot2c_f32_bf16_e32 v38, v10, v34
	ds_swizzle_b32 v7, v7 offset:swizzle(SWAP,8)
	s_nop 2
	v_add_f32_e32 v6, v60, v38
	global_load_dwordx4 v[128:131], v32, s[26:27]
	v_cndmask_b32_e64 v4, v41, v49, s[48:49]
	ds_swizzle_b32 v4, v4 offset:swizzle(SWAP,8)
	v_cndmask_b32_e64 v5, v42, v50, s[48:49]
	ds_swizzle_b32 v5, v5 offset:swizzle(SWAP,8)
	v_cndmask_b32_e64 v8, v44, v100, s[48:49]
	ds_swizzle_b32 v8, v8 offset:swizzle(SWAP,8)
	v_cndmask_b32_e64 v9, v45, v101, s[48:49]
	ds_swizzle_b32 v9, v9 offset:swizzle(SWAP,8)
	v_cndmask_b32_e64 v10, v46, v102, s[48:49]
	s_waitcnt lgkmcnt(3)
	v_add_f32_e32 v2, v2, v4
	v_cndmask_b32_e64 v4, v50, v42, s[48:49]
	ds_swizzle_b32 v10, v10 offset:swizzle(SWAP,8)
	v_cndmask_b32_e64 v11, v47, v62, s[48:49]
	s_waitcnt lgkmcnt(3)
	v_add_f32_e32 v4, v4, v5
	v_cndmask_b32_e64 v5, v51, v43, s[48:49]
	ds_swizzle_b32 v11, v11 offset:swizzle(SWAP,8)
	v_add_f32_e32 v5, v5, v7
	v_cndmask_b32_e64 v7, v100, v44, s[48:49]
	s_waitcnt lgkmcnt(3)
	v_add_f32_e32 v7, v7, v8
	v_cndmask_b32_e64 v8, v101, v45, s[48:49]
	s_waitcnt lgkmcnt(2)
	v_add_f32_e32 v8, v8, v9
	v_cndmask_b32_e64 v9, v102, v46, s[48:49]
	s_waitcnt lgkmcnt(1)
	v_add_f32_e32 v9, v9, v10
	v_cndmask_b32_e64 v10, v62, v47, s[48:49]
	s_waitcnt lgkmcnt(0)
	v_add_f32_e32 v10, v10, v11
	v_cndmask_b32_e64 v11, v6, v48, s[48:49]
	v_cndmask_b32_e64 v6, v48, v6, s[48:49]
	ds_swizzle_b32 v6, v6 offset:swizzle(SWAP,8)
	s_waitcnt lgkmcnt(0)
	v_add_f32_e32 v6, v11, v6
	v_cndmask_b32_e64 v11, v8, v2, s[46:47]
	v_cndmask_b32_e64 v2, v2, v8, s[46:47]
	v_cndmask_b32_e64 v8, v9, v4, s[46:47]
	v_cndmask_b32_e64 v4, v4, v9, s[46:47]
	ds_swizzle_b32 v4, v4 offset:swizzle(SWAP,4)
	ds_swizzle_b32 v2, v2 offset:swizzle(SWAP,4)
	s_waitcnt lgkmcnt(1)
	v_add_f32_e32 v4, v8, v4
	v_cndmask_b32_e64 v8, v10, v5, s[46:47]
	v_cndmask_b32_e64 v5, v5, v10, s[46:47]
	ds_swizzle_b32 v5, v5 offset:swizzle(SWAP,4)
	s_waitcnt lgkmcnt(1)
	v_add_f32_e32 v2, v11, v2
	s_waitcnt lgkmcnt(0)
	v_add_f32_e32 v5, v8, v5
	v_cndmask_b32_e64 v8, v6, v7, s[46:47]
	v_cndmask_b32_e64 v6, v7, v6, s[46:47]
	ds_swizzle_b32 v6, v6 offset:swizzle(SWAP,4)
	v_cndmask_b32_e64 v7, v5, v2, s[44:45]
	v_cndmask_b32_e64 v2, v2, v5, s[44:45]
	ds_swizzle_b32 v2, v2 offset:swizzle(SWAP,2)
	s_waitcnt lgkmcnt(1)
	v_add_f32_e32 v6, v8, v6
	v_cndmask_b32_e64 v5, v6, v4, s[44:45]
	v_cndmask_b32_e64 v4, v4, v6, s[44:45]
	ds_swizzle_b32 v4, v4 offset:swizzle(SWAP,2)
	s_waitcnt lgkmcnt(1)
	v_add_f32_e32 v2, v7, v2
	s_waitcnt lgkmcnt(0)
	v_add_f32_e32 v4, v5, v4
	v_cndmask_b32_e64 v5, v4, v2, s[42:43]
	v_cndmask_b32_e64 v2, v2, v4, s[42:43]
	ds_swizzle_b32 v2, v2 offset:swizzle(SWAP,1)
	s_waitcnt lgkmcnt(0)
	v_add_f32_e32 v2, v5, v2
	ds_swizzle_b32 v4, v2 offset:swizzle(SWAP,16)
	s_waitcnt lgkmcnt(0)
	v_add_f32_e32 v2, v2, v4
	v_mov_b32_e32 v4, v2
	s_nop 1
	v_permlane32_swap_b32_e32 v2, v4
	v_add_f32_e32 v6, v2, v4
	v_lshl_add_u32 v2, v40, 2, s14
	v_add_u32_e32 v4, 0xc0, v2
	ds_read2st64_b32 v[4:5], v4 offset0:9 offset1:17
	s_waitcnt lgkmcnt(0)
	v_mul_f32_e32 v4, v4, v6
	v_mul_f32_e32 v6, 0x3d372713, v4
	v_mul_f32_e32 v6, v4, v6
	v_fma_f32 v6, v4, v6, v4
	v_mul_f32_e32 v6, 0x3f4c422a, v6
	v_cmp_nlt_f32_e64 s[12:13], |v6|, s25
	s_and_saveexec_b64 s[26:27], s[12:13]
	s_xor_b64 s[12:13], exec, s[26:27]
	s_cbranch_execz .LBB0_543
	v_add_f32_e64 v7, |v6|, |v6|
	v_mul_f32_e32 v8, 0x3fb8aa3b, v7
	v_rndne_f32_e32 v9, v8
	v_sub_f32_e32 v10, v8, v9
	v_fma_f32 v8, v7, s70, -v8
	v_fmac_f32_e32 v8, 0x32a5705f, v7
	v_add_f32_e32 v8, v10, v8
	v_cvt_i32_f32_e32 v9, v9
	v_exp_f32_e32 v8, v8
	v_cmp_ngt_f32_e64 s[42:43], s67, v7
	v_ldexp_f32 v8, v8, v9
	s_nop 0
	v_cndmask_b32_e64 v8, 0, v8, s[42:43]
	v_cmp_nlt_f32_e64 s[42:43], s68, v7
	s_nop 1
	v_cndmask_b32_e64 v7, v205, v8, s[42:43]
	v_add_f32_e32 v7, 1.0, v7
	v_rcp_f32_e32 v7, v7
	s_nop 0
	v_fma_f32 v7, v7, -2.0, 1.0
	s_andn2_saveexec_b64 s[12:13], s[12:13]
	s_cbranch_execnz .LBB0_544

; #define P4_FOR16(M) M(0) M(1) M(2) M(3) M(4) M(5) M(6) M(7) M(8) M(9) M(10) M(11) M(12) M(13) M(14) M(15)
; #define P4_U(i) { P4_DOT(b##i, part[i]); const int nk_ = __builtin_amdgcn_readlane(ksel, nb + i); P4_LOAD(b##i, Ug, nk_); }
; #define P4_U(i) { P4_DOT(b##i, part[i]); const int nk_ = __builtin_amdgcn_readlane(kn, i); P4_LOAD(b##i, nbase, nk_); }
; __device__ __forceinline__ void peer_gather_f4p(const float* X, const int* __restrict__ IDX, const float* __restrict__ G, ...
;     ...
;         {
;     ...
;             P4_FOR16(P4_U)
.LBB0_1236:
	s_mov_b32 s87, s86
	s_waitcnt vmcnt(15)
	v_cvt_scalef32_pk_bf16_fp4 v42, v64, 1.0
	v_or_b32_e32 v40, s27, v44
	v_cvt_scalef32_pk_bf16_fp4 v44, v64, 1.0 op_sel:[1,0,0]
	v_cvt_scalef32_pk_bf16_fp4 v46, v64, 1.0 op_sel:[0,1,0]
	v_cvt_scalef32_pk_bf16_fp4 v48, v64, 1.0 op_sel:[1,1,0]
	v_dot2_f32_bf16 v50, v42, v6, 0
	v_dot2_f32_bf16 v42, v44, v4, 0
	v_dot2_f32_bf16 v50, v46, v10, v50
	s_cmp_eq_u32 s26, 3
	v_dot2_f32_bf16 v42, v48, v8, v42
	v_cvt_scalef32_pk_bf16_fp4 v44, v65, 1.0
	v_cvt_scalef32_pk_bf16_fp4 v46, v65, 1.0 op_sel:[1,0,0]
	v_cvt_scalef32_pk_bf16_fp4 v48, v65, 1.0 op_sel:[0,1,0]
	v_cvt_scalef32_pk_bf16_fp4 v52, v65, 1.0 op_sel:[1,1,0]
	v_readlane_b32 s26, v2, 0
	v_dot2_f32_bf16 v50, v44, v14, v50
	v_dot2_f32_bf16 v42, v46, v12, v42
	s_cselect_b32 s12, s53, s51
	v_dot2_f32_bf16 v50, v48, v18, v50
	v_dot2_f32_bf16 v42, v52, v16, v42
	v_cvt_scalef32_pk_bf16_fp4 v44, v66, 1.0
	v_cvt_scalef32_pk_bf16_fp4 v46, v66, 1.0 op_sel:[1,0,0]
	v_cvt_scalef32_pk_bf16_fp4 v48, v66, 1.0 op_sel:[0,1,0]
	v_cvt_scalef32_pk_bf16_fp4 v52, v66, 1.0 op_sel:[1,1,0]
	s_cselect_b32 s13, s52, s50
	v_dot2_f32_bf16 v50, v44, v22, v50
	v_dot2_f32_bf16 v42, v46, v20, v42
	s_lshr_b32 s26, s26, 7
	v_dot2_f32_bf16 v50, v48, v26, v50
	v_dot2_f32_bf16 v42, v52, v24, v42
	s_mov_b32 s27, s86
	v_cvt_scalef32_pk_bf16_fp4 v44, v67, 1.0
	v_cvt_scalef32_pk_bf16_fp4 v46, v67, 1.0 op_sel:[1,0,0]
	v_cvt_scalef32_pk_bf16_fp4 v48, v67, 1.0 op_sel:[0,1,0]
	v_cvt_scalef32_pk_bf16_fp4 v52, v67, 1.0 op_sel:[1,1,0]
	s_lshl_b64 s[26:27], s[26:27], 10
	v_dot2_f32_bf16 v50, v44, v30, v50
	v_dot2_f32_bf16 v42, v46, v28, v42
	s_add_u32 s26, s13, s26
	v_dot2_f32_bf16 v50, v48, v36, v50
	v_dot2_f32_bf16 v42, v52, v34, v42
	s_addc_u32 s27, s12, s27
	s_nop 2
	v_add_f32_e32 v41, v50, v42
	global_load_dwordx4 v[64:67], v32, s[26:27]
	s_waitcnt vmcnt(15)
	v_cvt_scalef32_pk_bf16_fp4 v42, v68, 1.0
	v_cvt_scalef32_pk_bf16_fp4 v44, v68, 1.0 op_sel:[1,0,0]
	v_cvt_scalef32_pk_bf16_fp4 v46, v68, 1.0 op_sel:[0,1,0]
	v_cvt_scalef32_pk_bf16_fp4 v48, v68, 1.0 op_sel:[1,1,0]
	v_dot2_f32_bf16 v50, v42, v6, 0
	v_dot2_f32_bf16 v42, v44, v4, 0
	v_dot2_f32_bf16 v50, v46, v10, v50
	v_readlane_b32 s26, v2, 1
	v_dot2_f32_bf16 v42, v48, v8, v42
	v_cvt_scalef32_pk_bf16_fp4 v44, v69, 1.0
	v_cvt_scalef32_pk_bf16_fp4 v46, v69, 1.0 op_sel:[1,0,0]
	v_cvt_scalef32_pk_bf16_fp4 v48, v69, 1.0 op_sel:[0,1,0]
	v_cvt_scalef32_pk_bf16_fp4 v52, v69, 1.0 op_sel:[1,1,0]
	s_lshr_b32 s26, s26, 7
	v_dot2_f32_bf16 v50, v44, v14, v50
	v_dot2_f32_bf16 v42, v46, v12, v42
	s_mov_b32 s27, s86
	v_dot2_f32_bf16 v50, v48, v18, v50
	v_dot2_f32_bf16 v42, v52, v16, v42
	v_cvt_scalef32_pk_bf16_fp4 v44, v70, 1.0
	v_cvt_scalef32_pk_bf16_fp4 v46, v70, 1.0 op_sel:[1,0,0]
	v_cvt_scalef32_pk_bf16_fp4 v48, v70, 1.0 op_sel:[0,1,0]
	v_cvt_scalef32_pk_bf16_fp4 v52, v70, 1.0 op_sel:[1,1,0]
	s_lshl_b64 s[26:27], s[26:27], 10
	v_dot2_f32_bf16 v50, v44, v22, v50
	v_dot2_f32_bf16 v42, v46, v20, v42
	s_add_u32 s26, s13, s26
	v_dot2_f32_bf16 v50, v48, v26, v50
	v_dot2_f32_bf16 v42, v52, v24, v42
	v_cvt_scalef32_pk_bf16_fp4 v44, v71, 1.0
	v_cvt_scalef32_pk_bf16_fp4 v46, v71, 1.0 op_sel:[1,0,0]
	v_cvt_scalef32_pk_bf16_fp4 v48, v71, 1.0 op_sel:[0,1,0]
	v_cvt_scalef32_pk_bf16_fp4 v52, v71, 1.0 op_sel:[1,1,0]
	s_addc_u32 s27, s12, s27
	v_dot2_f32_bf16 v50, v44, v30, v50
	v_dot2_f32_bf16 v42, v46, v28, v42
	v_mov_b32_e32 v38, 0
	v_dot2_f32_bf16 v50, v48, v36, v50
	v_dot2_f32_bf16 v42, v52, v34, v42
	s_nop 2
	v_add_f32_e32 v42, v50, v42
	global_load_dwordx4 v[68:71], v32, s[26:27]
	s_waitcnt vmcnt(15)
	v_cvt_scalef32_pk_bf16_fp4 v44, v72, 1.0
	v_cvt_scalef32_pk_bf16_fp4 v46, v72, 1.0 op_sel:[1,0,0]
	v_cvt_scalef32_pk_bf16_fp4 v48, v72, 1.0 op_sel:[0,1,0]
	v_cvt_scalef32_pk_bf16_fp4 v50, v72, 1.0 op_sel:[1,1,0]
	v_readlane_b32 s26, v2, 2
	v_dot2_f32_bf16 v52, v44, v6, 0
	v_dot2_f32_bf16 v44, v46, v4, 0
	v_dot2_f32_bf16 v52, v48, v10, v52
	s_lshr_b32 s26, s26, 7
	v_dot2_f32_bf16 v44, v50, v8, v44
	v_cvt_scalef32_pk_bf16_fp4 v46, v73, 1.0
	v_cvt_scalef32_pk_bf16_fp4 v48, v73, 1.0 op_sel:[1,0,0]
	v_cvt_scalef32_pk_bf16_fp4 v50, v73, 1.0 op_sel:[0,1,0]
	v_cvt_scalef32_pk_bf16_fp4 v54, v73, 1.0 op_sel:[1,1,0]
	s_mov_b32 s27, s86
	v_dot2_f32_bf16 v52, v46, v14, v52
	v_dot2_f32_bf16 v44, v48, v12, v44
	s_lshl_b64 s[26:27], s[26:27], 10
	v_dot2_f32_bf16 v52, v50, v18, v52
	v_dot2_f32_bf16 v44, v54, v16, v44
	v_cvt_scalef32_pk_bf16_fp4 v46, v74, 1.0
	v_cvt_scalef32_pk_bf16_fp4 v48, v74, 1.0 op_sel:[1,0,0]
	v_cvt_scalef32_pk_bf16_fp4 v50, v74, 1.0 op_sel:[0,1,0]
	v_cvt_scalef32_pk_bf16_fp4 v54, v74, 1.0 op_sel:[1,1,0]
	s_add_u32 s26, s13, s26
	v_dot2_f32_bf16 v52, v46, v22, v52
	v_dot2_f32_bf16 v44, v48, v20, v44
	s_addc_u32 s27, s12, s27
	v_dot2_f32_bf16 v52, v50, v26, v52
	v_dot2_f32_bf16 v44, v54, v24, v44
	v_cvt_scalef32_pk_bf16_fp4 v46, v75, 1.0
	v_cvt_scalef32_pk_bf16_fp4 v48, v75, 1.0 op_sel:[1,0,0]
	v_cvt_scalef32_pk_bf16_fp4 v50, v75, 1.0 op_sel:[0,1,0]
	v_cvt_scalef32_pk_bf16_fp4 v54, v75, 1.0 op_sel:[1,1,0]
	s_nop 0
	v_dot2_f32_bf16 v52, v46, v30, v52
	v_dot2_f32_bf16 v44, v48, v28, v44
	s_nop 0
	v_dot2_f32_bf16 v52, v50, v36, v52
	v_dot2_f32_bf16 v44, v54, v34, v44
	s_nop 0
	s_nop 2
	v_add_f32_e32 v43, v52, v44
	global_load_dwordx4 v[72:75], v32, s[26:27]
	s_waitcnt vmcnt(15)
; #define P4_FOR16(M) M(0) M(1) M(2) M(3) M(4) M(5) M(6) M(7) M(8) M(9) M(10) M(11) M(12) M(13) M(14) M(15)
; #define P4_U(i) { P4_DOT(b##i, part[i]); const int nk_ = __builtin_amdgcn_readlane(ksel, nb + i); P4_LOAD(b##i, Ug, nk_); }
; #define P4_U(i) { P4_DOT(b##i, part[i]); const int nk_ = __builtin_amdgcn_readlane(kn, i); P4_LOAD(b##i, nbase, nk_); }
; __device__ __forceinline__ void peer_gather_f4p(const float* X, const int* __restrict__ IDX, const float* __restrict__ G, ...
;     ...
;         {
;     ...
;             P4_FOR16(P4_U)
	v_cvt_scalef32_pk_bf16_fp4 v44, v76, 1.0
	v_cvt_scalef32_pk_bf16_fp4 v46, v76, 1.0 op_sel:[1,0,0]
	v_cvt_scalef32_pk_bf16_fp4 v48, v76, 1.0 op_sel:[0,1,0]
	v_cvt_scalef32_pk_bf16_fp4 v50, v76, 1.0 op_sel:[1,1,0]
	v_dot2_f32_bf16 v52, v44, v6, 0
	v_dot2_f32_bf16 v44, v46, v4, 0
	v_dot2_f32_bf16 v52, v48, v10, v52
	v_readlane_b32 s26, v2, 3
	v_dot2_f32_bf16 v44, v50, v8, v44
	v_cvt_scalef32_pk_bf16_fp4 v46, v77, 1.0
	v_cvt_scalef32_pk_bf16_fp4 v48, v77, 1.0 op_sel:[1,0,0]
	v_cvt_scalef32_pk_bf16_fp4 v50, v77, 1.0 op_sel:[0,1,0]
	v_cvt_scalef32_pk_bf16_fp4 v54, v77, 1.0 op_sel:[1,1,0]
	s_lshr_b32 s26, s26, 7
	v_dot2_f32_bf16 v52, v46, v14, v52
	v_dot2_f32_bf16 v44, v48, v12, v44
	s_mov_b32 s27, s86
	v_dot2_f32_bf16 v52, v50, v18, v52
	v_dot2_f32_bf16 v44, v54, v16, v44
	v_cvt_scalef32_pk_bf16_fp4 v46, v78, 1.0
	v_cvt_scalef32_pk_bf16_fp4 v48, v78, 1.0 op_sel:[1,0,0]
	v_cvt_scalef32_pk_bf16_fp4 v50, v78, 1.0 op_sel:[0,1,0]
	v_cvt_scalef32_pk_bf16_fp4 v54, v78, 1.0 op_sel:[1,1,0]
	s_lshl_b64 s[26:27], s[26:27], 10
	v_dot2_f32_bf16 v52, v46, v22, v52
	v_dot2_f32_bf16 v44, v48, v20, v44
	s_add_u32 s26, s13, s26
	v_dot2_f32_bf16 v52, v50, v26, v52
	v_dot2_f32_bf16 v44, v54, v24, v44
	v_cvt_scalef32_pk_bf16_fp4 v46, v79, 1.0
	v_cvt_scalef32_pk_bf16_fp4 v48, v79, 1.0 op_sel:[1,0,0]
	v_cvt_scalef32_pk_bf16_fp4 v50, v79, 1.0 op_sel:[0,1,0]
	v_cvt_scalef32_pk_bf16_fp4 v54, v79, 1.0 op_sel:[1,1,0]
	s_addc_u32 s27, s12, s27
	v_dot2_f32_bf16 v52, v46, v30, v52
	v_dot2_f32_bf16 v44, v48, v28, v44
	s_nop 0
	v_dot2_f32_bf16 v52, v50, v36, v52
	v_dot2_f32_bf16 v44, v54, v34, v44
	s_nop 2
	v_add_f32_e32 v44, v52, v44
	global_load_dwordx4 v[76:79], v32, s[26:27]
	s_waitcnt vmcnt(15)
	v_cvt_scalef32_pk_bf16_fp4 v46, v84, 1.0
	v_cvt_scalef32_pk_bf16_fp4 v48, v84, 1.0 op_sel:[1,0,0]
	v_cvt_scalef32_pk_bf16_fp4 v50, v84, 1.0 op_sel:[0,1,0]
	v_cvt_scalef32_pk_bf16_fp4 v52, v84, 1.0 op_sel:[1,1,0]
	v_readlane_b32 s26, v2, 4
	v_dot2_f32_bf16 v54, v46, v6, 0
	v_dot2_f32_bf16 v46, v48, v4, 0
	v_dot2_f32_bf16 v54, v50, v10, v54
	s_lshr_b32 s26, s26, 7
	v_dot2_f32_bf16 v46, v52, v8, v46
	v_cvt_scalef32_pk_bf16_fp4 v48, v85, 1.0
	v_cvt_scalef32_pk_bf16_fp4 v50, v85, 1.0 op_sel:[1,0,0]
	v_cvt_scalef32_pk_bf16_fp4 v52, v85, 1.0 op_sel:[0,1,0]
	v_cvt_scalef32_pk_bf16_fp4 v56, v85, 1.0 op_sel:[1,1,0]
	s_mov_b32 s27, s86
	v_dot2_f32_bf16 v54, v48, v14, v54
	v_dot2_f32_bf16 v46, v50, v12, v46
	s_lshl_b64 s[26:27], s[26:27], 10
	v_dot2_f32_bf16 v54, v52, v18, v54
	v_dot2_f32_bf16 v46, v56, v16, v46
	v_cvt_scalef32_pk_bf16_fp4 v48, v86, 1.0
	v_cvt_scalef32_pk_bf16_fp4 v50, v86, 1.0 op_sel:[1,0,0]
	v_cvt_scalef32_pk_bf16_fp4 v52, v86, 1.0 op_sel:[0,1,0]
	v_cvt_scalef32_pk_bf16_fp4 v56, v86, 1.0 op_sel:[1,1,0]
	s_add_u32 s26, s13, s26
	v_dot2_f32_bf16 v54, v48, v22, v54
	v_dot2_f32_bf16 v46, v50, v20, v46
	s_addc_u32 s27, s12, s27
	v_dot2_f32_bf16 v54, v52, v26, v54
	v_dot2_f32_bf16 v46, v56, v24, v46
	v_cvt_scalef32_pk_bf16_fp4 v48, v87, 1.0
	v_cvt_scalef32_pk_bf16_fp4 v50, v87, 1.0 op_sel:[1,0,0]
	v_cvt_scalef32_pk_bf16_fp4 v52, v87, 1.0 op_sel:[0,1,0]
	v_cvt_scalef32_pk_bf16_fp4 v56, v87, 1.0 op_sel:[1,1,0]
	s_nop 0
	v_dot2_f32_bf16 v54, v48, v30, v54
	v_dot2_f32_bf16 v46, v50, v28, v46
	s_nop 0
	v_dot2_f32_bf16 v54, v52, v36, v54
	v_dot2_f32_bf16 v46, v56, v34, v46
	s_nop 0
	s_nop 2
	v_add_f32_e32 v45, v54, v46
	global_load_dwordx4 v[84:87], v32, s[26:27]
	s_waitcnt vmcnt(15)
	v_cvt_scalef32_pk_bf16_fp4 v46, v88, 1.0
	v_cvt_scalef32_pk_bf16_fp4 v48, v88, 1.0 op_sel:[1,0,0]
	v_cvt_scalef32_pk_bf16_fp4 v50, v88, 1.0 op_sel:[0,1,0]
	v_cvt_scalef32_pk_bf16_fp4 v52, v88, 1.0 op_sel:[1,1,0]
	v_dot2_f32_bf16 v54, v46, v6, 0
	v_dot2_f32_bf16 v46, v48, v4, 0
	v_dot2_f32_bf16 v54, v50, v10, v54
	v_readlane_b32 s26, v2, 5
	v_dot2_f32_bf16 v46, v52, v8, v46
	v_cvt_scalef32_pk_bf16_fp4 v48, v89, 1.0
	v_cvt_scalef32_pk_bf16_fp4 v50, v89, 1.0 op_sel:[1,0,0]
	v_cvt_scalef32_pk_bf16_fp4 v52, v89, 1.0 op_sel:[0,1,0]
	v_cvt_scalef32_pk_bf16_fp4 v56, v89, 1.0 op_sel:[1,1,0]
	s_lshr_b32 s26, s26, 7
	v_dot2_f32_bf16 v54, v48, v14, v54
	v_dot2_f32_bf16 v46, v50, v12, v46
	s_mov_b32 s27, s86
	v_dot2_f32_bf16 v54, v52, v18, v54
	v_dot2_f32_bf16 v46, v56, v16, v46
	v_cvt_scalef32_pk_bf16_fp4 v48, v90, 1.0
	v_cvt_scalef32_pk_bf16_fp4 v50, v90, 1.0 op_sel:[1,0,0]
	v_cvt_scalef32_pk_bf16_fp4 v52, v90, 1.0 op_sel:[0,1,0]
	v_cvt_scalef32_pk_bf16_fp4 v56, v90, 1.0 op_sel:[1,1,0]
	s_lshl_b64 s[26:27], s[26:27], 10
	v_dot2_f32_bf16 v54, v48, v22, v54
	v_dot2_f32_bf16 v46, v50, v20, v46
	s_add_u32 s26, s13, s26
	v_dot2_f32_bf16 v54, v52, v26, v54
	v_dot2_f32_bf16 v46, v56, v24, v46
	v_cvt_scalef32_pk_bf16_fp4 v48, v91, 1.0
	v_cvt_scalef32_pk_bf16_fp4 v50, v91, 1.0 op_sel:[1,0,0]
	v_cvt_scalef32_pk_bf16_fp4 v52, v91, 1.0 op_sel:[0,1,0]
	v_cvt_scalef32_pk_bf16_fp4 v56, v91, 1.0 op_sel:[1,1,0]
	s_addc_u32 s27, s12, s27
	v_dot2_f32_bf16 v54, v48, v30, v54
	v_dot2_f32_bf16 v46, v50, v28, v46
	s_nop 0
	v_dot2_f32_bf16 v54, v52, v36, v54
	v_dot2_f32_bf16 v46, v56, v34, v46
	s_nop 2
	v_add_f32_e32 v46, v54, v46
	global_load_dwordx4 v[88:91], v32, s[26:27]
	s_waitcnt vmcnt(15)
; #define P4_FOR16(M) M(0) M(1) M(2) M(3) M(4) M(5) M(6) M(7) M(8) M(9) M(10) M(11) M(12) M(13) M(14) M(15)
; #define P4_U(i) { P4_DOT(b##i, part[i]); const int nk_ = __builtin_amdgcn_readlane(ksel, nb + i); P4_LOAD(b##i, Ug, nk_); }
; #define P4_U(i) { P4_DOT(b##i, part[i]); const int nk_ = __builtin_amdgcn_readlane(kn, i); P4_LOAD(b##i, nbase, nk_); }
; __device__ __forceinline__ void peer_gather_f4p(const float* X, const int* __restrict__ IDX, const float* __restrict__ G, ...
;     ...
;         {
;     ...
;             P4_FOR16(P4_U)
	v_cvt_scalef32_pk_bf16_fp4 v48, v92, 1.0
	v_cvt_scalef32_pk_bf16_fp4 v50, v92, 1.0 op_sel:[1,0,0]
	v_cvt_scalef32_pk_bf16_fp4 v52, v92, 1.0 op_sel:[0,1,0]
	v_cvt_scalef32_pk_bf16_fp4 v54, v92, 1.0 op_sel:[1,1,0]
	v_readlane_b32 s26, v2, 6
	v_dot2_f32_bf16 v56, v48, v6, 0
	v_dot2_f32_bf16 v48, v50, v4, 0
	v_dot2_f32_bf16 v56, v52, v10, v56
	s_lshr_b32 s26, s26, 7
	v_dot2_f32_bf16 v48, v54, v8, v48
	v_cvt_scalef32_pk_bf16_fp4 v50, v93, 1.0
	v_cvt_scalef32_pk_bf16_fp4 v52, v93, 1.0 op_sel:[1,0,0]
	v_cvt_scalef32_pk_bf16_fp4 v54, v93, 1.0 op_sel:[0,1,0]
	v_cvt_scalef32_pk_bf16_fp4 v58, v93, 1.0 op_sel:[1,1,0]
	s_mov_b32 s27, s86
	v_dot2_f32_bf16 v56, v50, v14, v56
	v_dot2_f32_bf16 v48, v52, v12, v48
	s_lshl_b64 s[26:27], s[26:27], 10
	v_dot2_f32_bf16 v56, v54, v18, v56
	v_dot2_f32_bf16 v48, v58, v16, v48
	v_cvt_scalef32_pk_bf16_fp4 v50, v94, 1.0
	v_cvt_scalef32_pk_bf16_fp4 v52, v94, 1.0 op_sel:[1,0,0]
	v_cvt_scalef32_pk_bf16_fp4 v54, v94, 1.0 op_sel:[0,1,0]
	v_cvt_scalef32_pk_bf16_fp4 v58, v94, 1.0 op_sel:[1,1,0]
	s_add_u32 s26, s13, s26
	v_dot2_f32_bf16 v56, v50, v22, v56
	v_dot2_f32_bf16 v48, v52, v20, v48
	s_addc_u32 s27, s12, s27
	v_dot2_f32_bf16 v56, v54, v26, v56
	v_dot2_f32_bf16 v48, v58, v24, v48
	v_cvt_scalef32_pk_bf16_fp4 v50, v95, 1.0
	v_cvt_scalef32_pk_bf16_fp4 v52, v95, 1.0 op_sel:[1,0,0]
	v_cvt_scalef32_pk_bf16_fp4 v54, v95, 1.0 op_sel:[0,1,0]
	v_cvt_scalef32_pk_bf16_fp4 v58, v95, 1.0 op_sel:[1,1,0]
	s_nop 0
	v_dot2_f32_bf16 v56, v50, v30, v56
	v_dot2_f32_bf16 v48, v52, v28, v48
	s_nop 0
	v_dot2_f32_bf16 v56, v54, v36, v56
	v_dot2_f32_bf16 v48, v58, v34, v48
	s_nop 0
	s_nop 2
	v_add_f32_e32 v47, v56, v48
	global_load_dwordx4 v[92:95], v32, s[26:27]
	s_waitcnt vmcnt(15)
	v_cvt_scalef32_pk_bf16_fp4 v48, v96, 1.0
	v_cvt_scalef32_pk_bf16_fp4 v50, v96, 1.0 op_sel:[1,0,0]
	v_cvt_scalef32_pk_bf16_fp4 v52, v96, 1.0 op_sel:[0,1,0]
	v_cvt_scalef32_pk_bf16_fp4 v54, v96, 1.0 op_sel:[1,1,0]
	v_dot2_f32_bf16 v56, v48, v6, 0
	v_dot2_f32_bf16 v48, v50, v4, 0
	v_dot2_f32_bf16 v56, v52, v10, v56
	v_readlane_b32 s26, v2, 7
	v_dot2_f32_bf16 v48, v54, v8, v48
	v_cvt_scalef32_pk_bf16_fp4 v50, v97, 1.0
	v_cvt_scalef32_pk_bf16_fp4 v52, v97, 1.0 op_sel:[1,0,0]
	v_cvt_scalef32_pk_bf16_fp4 v54, v97, 1.0 op_sel:[0,1,0]
	v_cvt_scalef32_pk_bf16_fp4 v58, v97, 1.0 op_sel:[1,1,0]
	s_lshr_b32 s26, s26, 7
	v_dot2_f32_bf16 v56, v50, v14, v56
	v_dot2_f32_bf16 v48, v52, v12, v48
	s_mov_b32 s27, s86
	v_dot2_f32_bf16 v56, v54, v18, v56
	v_dot2_f32_bf16 v48, v58, v16, v48
	v_cvt_scalef32_pk_bf16_fp4 v50, v98, 1.0
	v_cvt_scalef32_pk_bf16_fp4 v52, v98, 1.0 op_sel:[1,0,0]
	v_cvt_scalef32_pk_bf16_fp4 v54, v98, 1.0 op_sel:[0,1,0]
	v_cvt_scalef32_pk_bf16_fp4 v58, v98, 1.0 op_sel:[1,1,0]
	s_lshl_b64 s[26:27], s[26:27], 10
	v_dot2_f32_bf16 v56, v50, v22, v56
	v_dot2_f32_bf16 v48, v52, v20, v48
	s_add_u32 s26, s13, s26
	v_dot2_f32_bf16 v56, v54, v26, v56
	v_dot2_f32_bf16 v48, v58, v24, v48
	v_cvt_scalef32_pk_bf16_fp4 v50, v99, 1.0
	v_cvt_scalef32_pk_bf16_fp4 v52, v99, 1.0 op_sel:[1,0,0]
	v_cvt_scalef32_pk_bf16_fp4 v54, v99, 1.0 op_sel:[0,1,0]
	v_cvt_scalef32_pk_bf16_fp4 v58, v99, 1.0 op_sel:[1,1,0]
	s_addc_u32 s27, s12, s27
	v_dot2_f32_bf16 v56, v50, v30, v56
	v_dot2_f32_bf16 v48, v52, v28, v48
	s_nop 0
	v_dot2_f32_bf16 v56, v54, v36, v56
	v_dot2_f32_bf16 v48, v58, v34, v48
	s_nop 2
	v_add_f32_e32 v48, v56, v48
	global_load_dwordx4 v[96:99], v32, s[26:27]
	s_waitcnt vmcnt(15)
	v_cvt_scalef32_pk_bf16_fp4 v50, v100, 1.0
	v_cvt_scalef32_pk_bf16_fp4 v52, v100, 1.0 op_sel:[1,0,0]
	v_cvt_scalef32_pk_bf16_fp4 v54, v100, 1.0 op_sel:[0,1,0]
	v_cvt_scalef32_pk_bf16_fp4 v56, v100, 1.0 op_sel:[1,1,0]
	v_readlane_b32 s26, v2, 8
	v_dot2_f32_bf16 v58, v50, v6, 0
	v_dot2_f32_bf16 v50, v52, v4, 0
	v_dot2_f32_bf16 v58, v54, v10, v58
	s_lshr_b32 s26, s26, 7
	v_dot2_f32_bf16 v50, v56, v8, v50
	v_cvt_scalef32_pk_bf16_fp4 v52, v101, 1.0
	v_cvt_scalef32_pk_bf16_fp4 v54, v101, 1.0 op_sel:[1,0,0]
	v_cvt_scalef32_pk_bf16_fp4 v56, v101, 1.0 op_sel:[0,1,0]
	v_cvt_scalef32_pk_bf16_fp4 v60, v101, 1.0 op_sel:[1,1,0]
	s_mov_b32 s27, s86
	v_dot2_f32_bf16 v58, v52, v14, v58
	v_dot2_f32_bf16 v50, v54, v12, v50
	s_lshl_b64 s[26:27], s[26:27], 10
	v_dot2_f32_bf16 v58, v56, v18, v58
	v_dot2_f32_bf16 v50, v60, v16, v50
	v_cvt_scalef32_pk_bf16_fp4 v52, v102, 1.0
	v_cvt_scalef32_pk_bf16_fp4 v54, v102, 1.0 op_sel:[1,0,0]
	v_cvt_scalef32_pk_bf16_fp4 v56, v102, 1.0 op_sel:[0,1,0]
	v_cvt_scalef32_pk_bf16_fp4 v60, v102, 1.0 op_sel:[1,1,0]
	s_add_u32 s26, s13, s26
	v_dot2_f32_bf16 v58, v52, v22, v58
	v_dot2_f32_bf16 v50, v54, v20, v50
	s_addc_u32 s27, s12, s27
	v_dot2_f32_bf16 v58, v56, v26, v58
	v_dot2_f32_bf16 v50, v60, v24, v50
	v_cvt_scalef32_pk_bf16_fp4 v52, v103, 1.0
	v_cvt_scalef32_pk_bf16_fp4 v54, v103, 1.0 op_sel:[1,0,0]
	v_cvt_scalef32_pk_bf16_fp4 v56, v103, 1.0 op_sel:[0,1,0]
	v_cvt_scalef32_pk_bf16_fp4 v60, v103, 1.0 op_sel:[1,1,0]
	s_nop 0
	v_dot2_f32_bf16 v58, v52, v30, v58
	v_dot2_f32_bf16 v50, v54, v28, v50
	s_nop 0
	v_dot2_f32_bf16 v58, v56, v36, v58
	v_dot2_f32_bf16 v50, v60, v34, v50
	s_nop 0
	s_nop 2
	v_add_f32_e32 v49, v58, v50
	global_load_dwordx4 v[100:103], v32, s[26:27]
	s_waitcnt vmcnt(15)
; #define P4_FOR16(M) M(0) M(1) M(2) M(3) M(4) M(5) M(6) M(7) M(8) M(9) M(10) M(11) M(12) M(13) M(14) M(15)
; #define P4_U(i) { P4_DOT(b##i, part[i]); const int nk_ = __builtin_amdgcn_readlane(ksel, nb + i); P4_LOAD(b##i, Ug, nk_); }
; #define P4_U(i) { P4_DOT(b##i, part[i]); const int nk_ = __builtin_amdgcn_readlane(kn, i); P4_LOAD(b##i, nbase, nk_); }
; __device__ __forceinline__ void peer_gather_f4p(const float* X, const int* __restrict__ IDX, const float* __restrict__ G, ...
;     ...
;         {
;     ...
;             P4_FOR16(P4_U)
	v_cvt_scalef32_pk_bf16_fp4 v50, v104, 1.0
	v_cvt_scalef32_pk_bf16_fp4 v52, v104, 1.0 op_sel:[1,0,0]
	v_cvt_scalef32_pk_bf16_fp4 v54, v104, 1.0 op_sel:[0,1,0]
	v_cvt_scalef32_pk_bf16_fp4 v56, v104, 1.0 op_sel:[1,1,0]
	v_dot2_f32_bf16 v58, v50, v6, 0
	v_dot2_f32_bf16 v50, v52, v4, 0
	v_dot2_f32_bf16 v58, v54, v10, v58
	v_readlane_b32 s26, v2, 9
	v_dot2_f32_bf16 v50, v56, v8, v50
	v_cvt_scalef32_pk_bf16_fp4 v52, v105, 1.0
	v_cvt_scalef32_pk_bf16_fp4 v54, v105, 1.0 op_sel:[1,0,0]
	v_cvt_scalef32_pk_bf16_fp4 v56, v105, 1.0 op_sel:[0,1,0]
	v_cvt_scalef32_pk_bf16_fp4 v60, v105, 1.0 op_sel:[1,1,0]
	s_lshr_b32 s26, s26, 7
	v_dot2_f32_bf16 v58, v52, v14, v58
	v_dot2_f32_bf16 v50, v54, v12, v50
	s_mov_b32 s27, s86
	v_dot2_f32_bf16 v58, v56, v18, v58
	v_dot2_f32_bf16 v50, v60, v16, v50
	v_cvt_scalef32_pk_bf16_fp4 v52, v106, 1.0
	v_cvt_scalef32_pk_bf16_fp4 v54, v106, 1.0 op_sel:[1,0,0]
	v_cvt_scalef32_pk_bf16_fp4 v56, v106, 1.0 op_sel:[0,1,0]
	v_cvt_scalef32_pk_bf16_fp4 v60, v106, 1.0 op_sel:[1,1,0]
	s_lshl_b64 s[26:27], s[26:27], 10
	v_dot2_f32_bf16 v58, v52, v22, v58
	v_dot2_f32_bf16 v50, v54, v20, v50
	s_add_u32 s26, s13, s26
	v_dot2_f32_bf16 v58, v56, v26, v58
	v_dot2_f32_bf16 v50, v60, v24, v50
	v_cvt_scalef32_pk_bf16_fp4 v52, v107, 1.0
	v_cvt_scalef32_pk_bf16_fp4 v54, v107, 1.0 op_sel:[1,0,0]
	v_cvt_scalef32_pk_bf16_fp4 v56, v107, 1.0 op_sel:[0,1,0]
	v_cvt_scalef32_pk_bf16_fp4 v60, v107, 1.0 op_sel:[1,1,0]
	s_addc_u32 s27, s12, s27
	v_dot2_f32_bf16 v58, v52, v30, v58
	v_dot2_f32_bf16 v50, v54, v28, v50
	s_nop 0
	v_dot2_f32_bf16 v58, v56, v36, v58
	v_dot2_f32_bf16 v50, v60, v34, v50
	s_nop 2
	v_add_f32_e32 v50, v58, v50
	global_load_dwordx4 v[104:107], v32, s[26:27]
	s_waitcnt vmcnt(15)
	v_cvt_scalef32_pk_bf16_fp4 v52, v108, 1.0
	v_cvt_scalef32_pk_bf16_fp4 v54, v108, 1.0 op_sel:[1,0,0]
	v_cvt_scalef32_pk_bf16_fp4 v56, v108, 1.0 op_sel:[0,1,0]
	v_cvt_scalef32_pk_bf16_fp4 v58, v108, 1.0 op_sel:[1,1,0]
	v_readlane_b32 s26, v2, 10
	v_dot2_f32_bf16 v60, v52, v6, 0
	v_dot2_f32_bf16 v52, v54, v4, 0
	v_dot2_f32_bf16 v60, v56, v10, v60
	s_lshr_b32 s26, s26, 7
	v_dot2_f32_bf16 v52, v58, v8, v52
	v_cvt_scalef32_pk_bf16_fp4 v54, v109, 1.0
	v_cvt_scalef32_pk_bf16_fp4 v56, v109, 1.0 op_sel:[1,0,0]
	v_cvt_scalef32_pk_bf16_fp4 v58, v109, 1.0 op_sel:[0,1,0]
	v_cvt_scalef32_pk_bf16_fp4 v62, v109, 1.0 op_sel:[1,1,0]
	s_mov_b32 s27, s86
	v_dot2_f32_bf16 v60, v54, v14, v60
	v_dot2_f32_bf16 v52, v56, v12, v52
	s_lshl_b64 s[26:27], s[26:27], 10
	v_dot2_f32_bf16 v60, v58, v18, v60
	v_dot2_f32_bf16 v52, v62, v16, v52
	v_cvt_scalef32_pk_bf16_fp4 v54, v110, 1.0
	v_cvt_scalef32_pk_bf16_fp4 v56, v110, 1.0 op_sel:[1,0,0]
	v_cvt_scalef32_pk_bf16_fp4 v58, v110, 1.0 op_sel:[0,1,0]
	v_cvt_scalef32_pk_bf16_fp4 v62, v110, 1.0 op_sel:[1,1,0]
	s_add_u32 s26, s13, s26
	v_dot2_f32_bf16 v60, v54, v22, v60
	v_dot2_f32_bf16 v52, v56, v20, v52
	s_addc_u32 s27, s12, s27
	v_dot2_f32_bf16 v60, v58, v26, v60
	v_dot2_f32_bf16 v52, v62, v24, v52
	v_cvt_scalef32_pk_bf16_fp4 v54, v111, 1.0
	v_cvt_scalef32_pk_bf16_fp4 v56, v111, 1.0 op_sel:[1,0,0]
	v_cvt_scalef32_pk_bf16_fp4 v58, v111, 1.0 op_sel:[0,1,0]
	v_cvt_scalef32_pk_bf16_fp4 v62, v111, 1.0 op_sel:[1,1,0]
	s_nop 0
	v_dot2_f32_bf16 v60, v54, v30, v60
	v_dot2_f32_bf16 v52, v56, v28, v52
	s_nop 0
	v_dot2_f32_bf16 v60, v58, v36, v60
	v_dot2_f32_bf16 v52, v62, v34, v52
	s_nop 0
	s_nop 2
	v_add_f32_e32 v51, v60, v52
	global_load_dwordx4 v[108:111], v32, s[26:27]
	s_waitcnt vmcnt(15)
	v_cvt_scalef32_pk_bf16_fp4 v52, v112, 1.0
	v_cvt_scalef32_pk_bf16_fp4 v54, v112, 1.0 op_sel:[1,0,0]
	v_cvt_scalef32_pk_bf16_fp4 v56, v112, 1.0 op_sel:[0,1,0]
	v_cvt_scalef32_pk_bf16_fp4 v58, v112, 1.0 op_sel:[1,1,0]
	v_dot2_f32_bf16 v60, v52, v6, 0
	v_dot2_f32_bf16 v52, v54, v4, 0
	v_dot2_f32_bf16 v60, v56, v10, v60
	v_readlane_b32 s26, v2, 11
	v_dot2_f32_bf16 v52, v58, v8, v52
	v_cvt_scalef32_pk_bf16_fp4 v54, v113, 1.0
	v_cvt_scalef32_pk_bf16_fp4 v56, v113, 1.0 op_sel:[1,0,0]
	v_cvt_scalef32_pk_bf16_fp4 v58, v113, 1.0 op_sel:[0,1,0]
	v_cvt_scalef32_pk_bf16_fp4 v62, v113, 1.0 op_sel:[1,1,0]
	s_lshr_b32 s26, s26, 7
	v_dot2_f32_bf16 v60, v54, v14, v60
	v_dot2_f32_bf16 v52, v56, v12, v52
	s_mov_b32 s27, s86
	v_dot2_f32_bf16 v60, v58, v18, v60
	v_dot2_f32_bf16 v52, v62, v16, v52
	v_cvt_scalef32_pk_bf16_fp4 v54, v114, 1.0
	v_cvt_scalef32_pk_bf16_fp4 v56, v114, 1.0 op_sel:[1,0,0]
	v_cvt_scalef32_pk_bf16_fp4 v58, v114, 1.0 op_sel:[0,1,0]
	v_cvt_scalef32_pk_bf16_fp4 v62, v114, 1.0 op_sel:[1,1,0]
	s_lshl_b64 s[26:27], s[26:27], 10
	v_dot2_f32_bf16 v60, v54, v22, v60
	v_dot2_f32_bf16 v52, v56, v20, v52
	s_add_u32 s26, s13, s26
	v_dot2_f32_bf16 v60, v58, v26, v60
	v_dot2_f32_bf16 v52, v62, v24, v52
	v_cvt_scalef32_pk_bf16_fp4 v54, v115, 1.0
	v_cvt_scalef32_pk_bf16_fp4 v56, v115, 1.0 op_sel:[1,0,0]
	v_cvt_scalef32_pk_bf16_fp4 v58, v115, 1.0 op_sel:[0,1,0]
	v_cvt_scalef32_pk_bf16_fp4 v62, v115, 1.0 op_sel:[1,1,0]
	s_addc_u32 s27, s12, s27
	v_dot2_f32_bf16 v60, v54, v30, v60
	v_dot2_f32_bf16 v52, v56, v28, v52
	s_nop 0
	v_dot2_f32_bf16 v60, v58, v36, v60
	v_dot2_f32_bf16 v52, v62, v34, v52
	s_nop 0
	s_nop 2
	v_add_f32_e32 v80, v60, v52
	global_load_dwordx4 v[112:115], v32, s[26:27]
	s_waitcnt vmcnt(15)
; #define P4_FOR16(M) M(0) M(1) M(2) M(3) M(4) M(5) M(6) M(7) M(8) M(9) M(10) M(11) M(12) M(13) M(14) M(15)
; #define P4_U(i) { P4_DOT(b##i, part[i]); const int nk_ = __builtin_amdgcn_readlane(ksel, nb + i); P4_LOAD(b##i, Ug, nk_); }
; #define P4_U(i) { P4_DOT(b##i, part[i]); const int nk_ = __builtin_amdgcn_readlane(kn, i); P4_LOAD(b##i, nbase, nk_); }
; __device__ __forceinline__ void peer_gather_f4p(const float* X, const int* __restrict__ IDX, const float* __restrict__ G, ...
;     ...
;         {
;     ...
;             P4_FOR16(P4_U)
	v_cvt_scalef32_pk_bf16_fp4 v52, v116, 1.0
	v_cvt_scalef32_pk_bf16_fp4 v54, v116, 1.0 op_sel:[1,0,0]
	v_cvt_scalef32_pk_bf16_fp4 v56, v116, 1.0 op_sel:[0,1,0]
	v_cvt_scalef32_pk_bf16_fp4 v58, v116, 1.0 op_sel:[1,1,0]
	v_dot2_f32_bf16 v60, v52, v6, 0
	v_dot2_f32_bf16 v52, v54, v4, 0
	v_dot2_f32_bf16 v60, v56, v10, v60
	v_readlane_b32 s26, v2, 12
	v_dot2_f32_bf16 v52, v58, v8, v52
	v_cvt_scalef32_pk_bf16_fp4 v54, v117, 1.0
	v_cvt_scalef32_pk_bf16_fp4 v56, v117, 1.0 op_sel:[1,0,0]
	v_cvt_scalef32_pk_bf16_fp4 v58, v117, 1.0 op_sel:[0,1,0]
	v_cvt_scalef32_pk_bf16_fp4 v62, v117, 1.0 op_sel:[1,1,0]
	s_lshr_b32 s26, s26, 7
	v_dot2_f32_bf16 v60, v54, v14, v60
	v_dot2_f32_bf16 v52, v56, v12, v52
	s_mov_b32 s27, s86
	v_dot2_f32_bf16 v60, v58, v18, v60
	v_dot2_f32_bf16 v52, v62, v16, v52
	v_cvt_scalef32_pk_bf16_fp4 v54, v118, 1.0
	v_cvt_scalef32_pk_bf16_fp4 v56, v118, 1.0 op_sel:[1,0,0]
	v_cvt_scalef32_pk_bf16_fp4 v58, v118, 1.0 op_sel:[0,1,0]
	v_cvt_scalef32_pk_bf16_fp4 v62, v118, 1.0 op_sel:[1,1,0]
	s_lshl_b64 s[26:27], s[26:27], 10
	v_dot2_f32_bf16 v60, v54, v22, v60
	v_dot2_f32_bf16 v52, v56, v20, v52
	s_add_u32 s26, s13, s26
	v_dot2_f32_bf16 v60, v58, v26, v60
	v_dot2_f32_bf16 v52, v62, v24, v52
	v_cvt_scalef32_pk_bf16_fp4 v54, v119, 1.0
	v_cvt_scalef32_pk_bf16_fp4 v56, v119, 1.0 op_sel:[1,0,0]
	v_cvt_scalef32_pk_bf16_fp4 v58, v119, 1.0 op_sel:[0,1,0]
	v_cvt_scalef32_pk_bf16_fp4 v62, v119, 1.0 op_sel:[1,1,0]
	s_addc_u32 s27, s12, s27
	v_dot2_f32_bf16 v60, v54, v30, v60
	v_dot2_f32_bf16 v52, v56, v28, v52
	s_nop 0
	v_dot2_f32_bf16 v60, v58, v36, v60
	v_dot2_f32_bf16 v52, v62, v34, v52
	s_nop 0
	s_nop 2
	v_add_f32_e32 v81, v60, v52
	global_load_dwordx4 v[116:119], v32, s[26:27]
	s_waitcnt vmcnt(15)
	v_cvt_scalef32_pk_bf16_fp4 v52, v120, 1.0
	v_cvt_scalef32_pk_bf16_fp4 v54, v120, 1.0 op_sel:[1,0,0]
	v_cvt_scalef32_pk_bf16_fp4 v56, v120, 1.0 op_sel:[0,1,0]
	v_cvt_scalef32_pk_bf16_fp4 v58, v120, 1.0 op_sel:[1,1,0]
	v_dot2_f32_bf16 v60, v52, v6, 0
	v_dot2_f32_bf16 v52, v54, v4, 0
	v_dot2_f32_bf16 v60, v56, v10, v60
	v_readlane_b32 s26, v2, 13
	v_dot2_f32_bf16 v52, v58, v8, v52
	v_cvt_scalef32_pk_bf16_fp4 v54, v121, 1.0
	v_cvt_scalef32_pk_bf16_fp4 v56, v121, 1.0 op_sel:[1,0,0]
	v_cvt_scalef32_pk_bf16_fp4 v58, v121, 1.0 op_sel:[0,1,0]
	v_cvt_scalef32_pk_bf16_fp4 v62, v121, 1.0 op_sel:[1,1,0]
	s_lshr_b32 s26, s26, 7
	v_dot2_f32_bf16 v60, v54, v14, v60
	v_dot2_f32_bf16 v52, v56, v12, v52
	s_mov_b32 s27, s86
	v_dot2_f32_bf16 v60, v58, v18, v60
	v_dot2_f32_bf16 v52, v62, v16, v52
	v_cvt_scalef32_pk_bf16_fp4 v54, v122, 1.0
	v_cvt_scalef32_pk_bf16_fp4 v56, v122, 1.0 op_sel:[1,0,0]
	v_cvt_scalef32_pk_bf16_fp4 v58, v122, 1.0 op_sel:[0,1,0]
	v_cvt_scalef32_pk_bf16_fp4 v62, v122, 1.0 op_sel:[1,1,0]
	s_lshl_b64 s[26:27], s[26:27], 10
	v_dot2_f32_bf16 v60, v54, v22, v60
	v_dot2_f32_bf16 v52, v56, v20, v52
	s_add_u32 s26, s13, s26
	v_dot2_f32_bf16 v60, v58, v26, v60
	v_dot2_f32_bf16 v52, v62, v24, v52
	v_cvt_scalef32_pk_bf16_fp4 v54, v123, 1.0
	v_cvt_scalef32_pk_bf16_fp4 v56, v123, 1.0 op_sel:[1,0,0]
	v_cvt_scalef32_pk_bf16_fp4 v58, v123, 1.0 op_sel:[0,1,0]
	v_cvt_scalef32_pk_bf16_fp4 v62, v123, 1.0 op_sel:[1,1,0]
	s_addc_u32 s27, s12, s27
	v_dot2_f32_bf16 v60, v54, v30, v60
	v_dot2_f32_bf16 v52, v56, v28, v52
	s_nop 0
	v_dot2_f32_bf16 v60, v58, v36, v60
	v_dot2_f32_bf16 v52, v62, v34, v52
	s_nop 0
	s_nop 2
	v_add_f32_e32 v82, v60, v52
	global_load_dwordx4 v[120:123], v32, s[26:27]
	s_waitcnt vmcnt(15)
	v_cvt_scalef32_pk_bf16_fp4 v52, v124, 1.0
	v_cvt_scalef32_pk_bf16_fp4 v54, v124, 1.0 op_sel:[1,0,0]
	v_cvt_scalef32_pk_bf16_fp4 v56, v124, 1.0 op_sel:[0,1,0]
	v_cvt_scalef32_pk_bf16_fp4 v58, v124, 1.0 op_sel:[1,1,0]
	v_dot2_f32_bf16 v60, v52, v6, 0
	v_dot2_f32_bf16 v52, v54, v4, 0
	v_dot2_f32_bf16 v60, v56, v10, v60
	v_readlane_b32 s26, v2, 14
	v_dot2_f32_bf16 v52, v58, v8, v52
	v_cvt_scalef32_pk_bf16_fp4 v54, v125, 1.0
	v_cvt_scalef32_pk_bf16_fp4 v56, v125, 1.0 op_sel:[1,0,0]
	v_cvt_scalef32_pk_bf16_fp4 v58, v125, 1.0 op_sel:[0,1,0]
	v_cvt_scalef32_pk_bf16_fp4 v62, v125, 1.0 op_sel:[1,1,0]
	s_lshr_b32 s26, s26, 7
	v_dot2_f32_bf16 v60, v54, v14, v60
	v_dot2_f32_bf16 v52, v56, v12, v52
	s_mov_b32 s27, s86
	v_dot2_f32_bf16 v60, v58, v18, v60
	v_dot2_f32_bf16 v52, v62, v16, v52
	v_cvt_scalef32_pk_bf16_fp4 v54, v126, 1.0
	v_cvt_scalef32_pk_bf16_fp4 v56, v126, 1.0 op_sel:[1,0,0]
	v_cvt_scalef32_pk_bf16_fp4 v58, v126, 1.0 op_sel:[0,1,0]
	v_cvt_scalef32_pk_bf16_fp4 v62, v126, 1.0 op_sel:[1,1,0]
	s_lshl_b64 s[26:27], s[26:27], 10
	v_dot2_f32_bf16 v60, v54, v22, v60
	v_dot2_f32_bf16 v52, v56, v20, v52
	s_add_u32 s26, s13, s26
	v_dot2_f32_bf16 v60, v58, v26, v60
	v_dot2_f32_bf16 v52, v62, v24, v52
	v_cvt_scalef32_pk_bf16_fp4 v54, v127, 1.0
	v_cvt_scalef32_pk_bf16_fp4 v56, v127, 1.0 op_sel:[1,0,0]
	v_cvt_scalef32_pk_bf16_fp4 v58, v127, 1.0 op_sel:[0,1,0]
	v_cvt_scalef32_pk_bf16_fp4 v62, v127, 1.0 op_sel:[1,1,0]
	s_addc_u32 s27, s12, s27
	v_dot2_f32_bf16 v60, v54, v30, v60
	v_dot2_f32_bf16 v52, v56, v28, v52
	s_nop 0
	v_dot2_f32_bf16 v60, v58, v36, v60
	v_dot2_f32_bf16 v52, v62, v34, v52
	s_nop 0
	s_nop 2
	v_add_f32_e32 v62, v60, v52
	global_load_dwordx4 v[124:127], v32, s[26:27]
	s_waitcnt vmcnt(15)
	v_cvt_scalef32_pk_bf16_fp4 v52, v128, 1.0
	v_cvt_scalef32_pk_bf16_fp4 v54, v128, 1.0 op_sel:[1,0,0]
	v_cvt_scalef32_pk_bf16_fp4 v56, v128, 1.0 op_sel:[0,1,0]
	v_cvt_scalef32_pk_bf16_fp4 v58, v128, 1.0 op_sel:[1,1,0]
	v_readlane_b32 s26, v2, 15
	v_dot2_f32_bf16 v60, v52, v6, 0
	v_dot2c_f32_bf16_e32 v38, v54, v4
	s_lshr_b32 s26, s26, 7
	v_dot2_f32_bf16 v60, v56, v10, v60
	v_dot2c_f32_bf16_e32 v38, v58, v8
	v_cvt_scalef32_pk_bf16_fp4 v4, v129, 1.0
	v_cvt_scalef32_pk_bf16_fp4 v6, v129, 1.0 op_sel:[1,0,0]
	v_cvt_scalef32_pk_bf16_fp4 v8, v129, 1.0 op_sel:[0,1,0]
	v_cvt_scalef32_pk_bf16_fp4 v10, v129, 1.0 op_sel:[1,1,0]
	s_mov_b32 s27, s86
	v_dot2_f32_bf16 v60, v4, v14, v60
	v_dot2c_f32_bf16_e32 v38, v6, v12
	s_lshl_b64 s[26:27], s[26:27], 10
	v_dot2_f32_bf16 v60, v8, v18, v60
	v_dot2c_f32_bf16_e32 v38, v10, v16
	v_cvt_scalef32_pk_bf16_fp4 v4, v130, 1.0
	v_cvt_scalef32_pk_bf16_fp4 v6, v130, 1.0 op_sel:[1,0,0]
	v_cvt_scalef32_pk_bf16_fp4 v8, v130, 1.0 op_sel:[0,1,0]
	v_cvt_scalef32_pk_bf16_fp4 v10, v130, 1.0 op_sel:[1,1,0]
	s_add_u32 s26, s13, s26
	v_dot2_f32_bf16 v60, v4, v22, v60
	v_dot2c_f32_bf16_e32 v38, v6, v20
	s_addc_u32 s27, s12, s27
	v_dot2_f32_bf16 v60, v8, v26, v60
	v_dot2c_f32_bf16_e32 v38, v10, v24
	v_cvt_scalef32_pk_bf16_fp4 v4, v131, 1.0
	v_cvt_scalef32_pk_bf16_fp4 v6, v131, 1.0 op_sel:[1,0,0]
	v_cvt_scalef32_pk_bf16_fp4 v8, v131, 1.0 op_sel:[0,1,0]
	v_cvt_scalef32_pk_bf16_fp4 v10, v131, 1.0 op_sel:[1,1,0]
	v_cndmask_b32_e64 v2, v49, v41, s[46:47]
	v_dot2_f32_bf16 v60, v4, v30, v60
	v_dot2c_f32_bf16_e32 v38, v6, v28
	v_cndmask_b32_e64 v7, v43, v51, s[46:47]
	v_dot2_f32_bf16 v60, v8, v36, v60
	v_dot2c_f32_bf16_e32 v38, v10, v34
	ds_swizzle_b32 v7, v7 offset:swizzle(SWAP,8)
	s_nop 2
	v_add_f32_e32 v6, v60, v38
	global_load_dwordx4 v[128:131], v32, s[26:27]
	v_cndmask_b32_e64 v4, v41, v49, s[46:47]
	ds_swizzle_b32 v4, v4 offset:swizzle(SWAP,8)
	v_cndmask_b32_e64 v5, v42, v50, s[46:47]
	ds_swizzle_b32 v5, v5 offset:swizzle(SWAP,8)
	v_cndmask_b32_e64 v8, v44, v80, s[46:47]
	ds_swizzle_b32 v8, v8 offset:swizzle(SWAP,8)
	v_cndmask_b32_e64 v9, v45, v81, s[46:47]
	ds_swizzle_b32 v9, v9 offset:swizzle(SWAP,8)
	v_cndmask_b32_e64 v10, v46, v82, s[46:47]
	s_waitcnt lgkmcnt(3)
	v_add_f32_e32 v2, v2, v4
	v_cndmask_b32_e64 v4, v50, v42, s[46:47]
	ds_swizzle_b32 v10, v10 offset:swizzle(SWAP,8)
	v_cndmask_b32_e64 v11, v47, v62, s[46:47]
	s_waitcnt lgkmcnt(3)
	v_add_f32_e32 v4, v4, v5
	v_cndmask_b32_e64 v5, v51, v43, s[46:47]
	ds_swizzle_b32 v11, v11 offset:swizzle(SWAP,8)
	v_add_f32_e32 v5, v5, v7
	v_cndmask_b32_e64 v7, v80, v44, s[46:47]
	s_waitcnt lgkmcnt(3)
	v_add_f32_e32 v7, v7, v8
	v_cndmask_b32_e64 v8, v81, v45, s[46:47]
	s_waitcnt lgkmcnt(2)
	v_add_f32_e32 v8, v8, v9
	v_cndmask_b32_e64 v9, v82, v46, s[46:47]
	s_waitcnt lgkmcnt(1)
	v_add_f32_e32 v9, v9, v10
	v_cndmask_b32_e64 v10, v62, v47, s[46:47]
	s_waitcnt lgkmcnt(0)
	v_add_f32_e32 v10, v10, v11
	v_cndmask_b32_e64 v11, v6, v48, s[46:47]
	v_cndmask_b32_e64 v6, v48, v6, s[46:47]
	ds_swizzle_b32 v6, v6 offset:swizzle(SWAP,8)
	s_waitcnt lgkmcnt(0)
	v_add_f32_e32 v6, v11, v6
	v_cndmask_b32_e64 v11, v8, v2, s[44:45]
	v_cndmask_b32_e64 v2, v2, v8, s[44:45]
	v_cndmask_b32_e64 v8, v9, v4, s[44:45]
	v_cndmask_b32_e64 v4, v4, v9, s[44:45]
	ds_swizzle_b32 v4, v4 offset:swizzle(SWAP,4)
	ds_swizzle_b32 v2, v2 offset:swizzle(SWAP,4)
	s_waitcnt lgkmcnt(1)
	v_add_f32_e32 v4, v8, v4
	v_cndmask_b32_e64 v8, v10, v5, s[44:45]
	v_cndmask_b32_e64 v5, v5, v10, s[44:45]
	ds_swizzle_b32 v5, v5 offset:swizzle(SWAP,4)
	s_waitcnt lgkmcnt(1)
	v_add_f32_e32 v2, v11, v2
	s_waitcnt lgkmcnt(0)
	v_add_f32_e32 v5, v8, v5
	v_cndmask_b32_e64 v8, v6, v7, s[44:45]
	v_cndmask_b32_e64 v6, v7, v6, s[44:45]
	ds_swizzle_b32 v6, v6 offset:swizzle(SWAP,4)
	v_cndmask_b32_e64 v7, v5, v2, s[42:43]
	v_cndmask_b32_e64 v2, v2, v5, s[42:43]
	ds_swizzle_b32 v2, v2 offset:swizzle(SWAP,2)
	s_waitcnt lgkmcnt(1)
	v_add_f32_e32 v6, v8, v6
	v_cndmask_b32_e64 v5, v6, v4, s[42:43]
	v_cndmask_b32_e64 v4, v4, v6, s[42:43]
	ds_swizzle_b32 v4, v4 offset:swizzle(SWAP,2)
	s_waitcnt lgkmcnt(1)
	v_add_f32_e32 v2, v7, v2
	s_waitcnt lgkmcnt(0)
	v_add_f32_e32 v4, v5, v4
	v_cndmask_b32_e64 v5, v4, v2, s[40:41]
	v_cndmask_b32_e64 v2, v2, v4, s[40:41]
	ds_swizzle_b32 v2, v2 offset:swizzle(SWAP,1)
	s_waitcnt lgkmcnt(0)
	v_add_f32_e32 v2, v5, v2
	ds_swizzle_b32 v4, v2 offset:swizzle(SWAP,16)
	s_waitcnt lgkmcnt(0)
	v_add_f32_e32 v2, v2, v4
	v_mov_b32_e32 v4, v2
	s_nop 1
	v_permlane32_swap_b32_e32 v2, v4
	v_add_f32_e32 v6, v2, v4
	v_lshl_add_u32 v2, v40, 2, s14
	v_add_u32_e32 v4, 0xc0, v2
	ds_read2st64_b32 v[4:5], v4 offset0:9 offset1:17
	s_waitcnt lgkmcnt(0)
	v_mul_f32_e32 v4, v4, v6
	v_mul_f32_e32 v6, 0x3d372713, v4
	v_mul_f32_e32 v6, v4, v6
	v_fma_f32 v6, v4, v6, v4
	v_mul_f32_e32 v6, 0x3f4c422a, v6
	v_cmp_nlt_f32_e64 s[12:13], |v6|, s25
	s_and_saveexec_b64 s[26:27], s[12:13]
	s_xor_b64 s[12:13], exec, s[26:27]
	s_cbranch_execz .LBB0_1240
	v_add_f32_e64 v7, |v6|, |v6|
	v_mul_f32_e32 v8, 0x3fb8aa3b, v7
	v_rndne_f32_e32 v9, v8
	v_sub_f32_e32 v10, v8, v9
	v_fma_f32 v8, v7, s70, -v8
	v_fmac_f32_e32 v8, 0x32a5705f, v7
	v_add_f32_e32 v8, v10, v8
	v_cvt_i32_f32_e32 v9, v9
	v_exp_f32_e32 v8, v8
	v_cmp_ngt_f32_e64 s[40:41], s67, v7
	v_ldexp_f32 v8, v8, v9
	s_nop 0
	v_cndmask_b32_e64 v8, 0, v8, s[40:41]
	v_cmp_nlt_f32_e64 s[40:41], s68, v7
	s_nop 1
	v_cndmask_b32_e64 v7, v205, v8, s[40:41]
	v_add_f32_e32 v7, 1.0, v7
	v_rcp_f32_e32 v7, v7
	s_nop 0
	v_fma_f32 v7, v7, -2.0, 1.0
	s_andn2_saveexec_b64 s[12:13], s[12:13]
	s_cbranch_execnz .LBB0_1241
